# v52 with the per-phase s_setprio flips removed from the four GEMM K-loops (second measurement)
# speedup vs baseline: 1.0460x; 1.0460x over previous
.LBB0_262:
	ds_read_b128 v[128:131], v181
	ds_read_b128 v[132:135], v181 offset:1024
	ds_read_b128 v[136:139], v181 offset:2048
	ds_read_b128 v[140:143], v181 offset:3072
	s_add_u32 s6, s4, 0xfff80080
	s_addc_u32 s7, s5, -1
	s_cmp_eq_u32 s37, 28
	s_cselect_b32 s9, s10, s7
	s_cselect_b32 s8, s11, s6
	s_cselect_b32 s7, s20, s36
	s_cselect_b32 s6, s34, s35
	v_lshl_add_u64 v[176:177], s[4:5], 0, v[158:159]
	s_add_i32 m0, s44, 0xc000
	ds_read_b128 v[144:147], v182
	ds_read_b128 v[168:171], v182 offset:1024
	ds_read_b128 v[172:175], v182 offset:2048
	ds_read_b128 v[184:187], v182 offset:3072
	ds_read_b128 v[188:191], v182 offset:4096
	ds_read_b128 v[192:195], v182 offset:5120
	ds_read_b128 v[196:199], v182 offset:6144
	ds_read_b128 v[200:203], v182 offset:7168
	global_load_lds_dwordx4 v[176:177], off
	v_lshl_add_u64 v[176:177], s[4:5], 0, v[160:161]
	s_add_i32 m0, s44, 0xe000
	s_nop 0
	global_load_lds_dwordx4 v[176:177], off
	s_waitcnt lgkmcnt(8)
	s_barrier
	s_waitcnt lgkmcnt(0)
	s_waitcnt lgkmcnt(0)
	v_mfma_f32_16x16x32_bf16 v[124:127], v[128:131], v[144:147], v[124:127]
	v_mfma_f32_16x16x32_bf16 v[120:123], v[136:139], v[144:147], v[120:123]
	v_mfma_f32_16x16x32_bf16 v[108:111], v[128:131], v[172:175], v[108:111]
	v_mfma_f32_16x16x32_bf16 v[104:107], v[136:139], v[172:175], v[104:107]
	v_mfma_f32_16x16x32_bf16 v[92:95], v[128:131], v[188:191], v[92:95]
	v_mfma_f32_16x16x32_bf16 v[88:91], v[136:139], v[188:191], v[88:91]
	v_mfma_f32_16x16x32_bf16 v[76:79], v[128:131], v[196:199], v[76:79]
	v_mfma_f32_16x16x32_bf16 v[72:75], v[136:139], v[196:199], v[72:75]
	v_mfma_f32_16x16x32_bf16 v[124:127], v[132:135], v[168:171], v[124:127]
	v_mfma_f32_16x16x32_bf16 v[120:123], v[140:143], v[168:171], v[120:123]
	v_mfma_f32_16x16x32_bf16 v[108:111], v[132:135], v[184:187], v[108:111]
	v_mfma_f32_16x16x32_bf16 v[104:107], v[140:143], v[184:187], v[104:107]
	v_mfma_f32_16x16x32_bf16 v[92:95], v[132:135], v[192:195], v[92:95]
	v_mfma_f32_16x16x32_bf16 v[88:91], v[140:143], v[192:195], v[88:91]
	v_mfma_f32_16x16x32_bf16 v[76:79], v[132:135], v[200:203], v[76:79]
	v_mfma_f32_16x16x32_bf16 v[72:75], v[140:143], v[200:203], v[72:75]
	s_barrier
	s_add_i32 s39, s80, s33
	v_lshl_add_u64 v[176:177], s[6:7], 0, v[150:151]
	s_mov_b32 m0, s39
	ds_read_b128 v[204:207], v183
	ds_read_b128 v[210:213], v183 offset:1024
	ds_read_b128 v[214:217], v183 offset:2048
	ds_read_b128 v[218:221], v183 offset:3072
	global_load_lds_dwordx4 v[176:177], off
	v_lshl_add_u64 v[222:223], s[6:7], 0, v[154:155]
	s_add_i32 m0, s39, 0x2000
	s_nop 0
	global_load_lds_dwordx4 v[222:223], off
	s_barrier
	s_waitcnt lgkmcnt(0)
	s_waitcnt lgkmcnt(0)
	v_mfma_f32_16x16x32_bf16 v[116:119], v[204:207], v[144:147], v[116:119]
	v_mfma_f32_16x16x32_bf16 v[112:115], v[214:217], v[144:147], v[112:115]
	v_mfma_f32_16x16x32_bf16 v[100:103], v[204:207], v[172:175], v[100:103]
	v_mfma_f32_16x16x32_bf16 v[96:99], v[214:217], v[172:175], v[96:99]
	v_mfma_f32_16x16x32_bf16 v[84:87], v[204:207], v[188:191], v[84:87]
	v_mfma_f32_16x16x32_bf16 v[80:83], v[214:217], v[188:191], v[80:83]
	v_mfma_f32_16x16x32_bf16 v[68:71], v[204:207], v[196:199], v[68:71]
	v_mfma_f32_16x16x32_bf16 v[64:67], v[214:217], v[196:199], v[64:67]
	v_mfma_f32_16x16x32_bf16 v[116:119], v[210:213], v[168:171], v[116:119]
	v_mfma_f32_16x16x32_bf16 v[112:115], v[218:221], v[168:171], v[112:115]
	v_mfma_f32_16x16x32_bf16 v[100:103], v[210:213], v[184:187], v[100:103]
	v_mfma_f32_16x16x32_bf16 v[96:99], v[218:221], v[184:187], v[96:99]
	v_mfma_f32_16x16x32_bf16 v[84:87], v[210:213], v[192:195], v[84:87]
	v_mfma_f32_16x16x32_bf16 v[80:83], v[218:221], v[192:195], v[80:83]
	v_mfma_f32_16x16x32_bf16 v[68:71], v[210:213], v[200:203], v[68:71]
	v_mfma_f32_16x16x32_bf16 v[64:67], v[218:221], v[200:203], v[64:67]
	s_mov_b32 m0, s44
	v_lshl_add_u64 v[224:225], s[8:9], 0, v[148:149]
	s_barrier
	ds_read_b128 v[144:147], v182 offset:16384
	ds_read_b128 v[168:171], v182 offset:17408
	ds_read_b128 v[172:175], v182 offset:18432
	ds_read_b128 v[184:187], v182 offset:19456
	ds_read_b128 v[188:191], v182 offset:20480
	ds_read_b128 v[192:195], v182 offset:21504
	ds_read_b128 v[196:199], v182 offset:22528
	ds_read_b128 v[200:203], v182 offset:23552
	global_load_lds_dwordx4 v[224:225], off
	v_lshl_add_u64 v[226:227], s[8:9], 0, v[152:153]
	s_mov_b32 m0, s45
	s_nop 0
	global_load_lds_dwordx4 v[226:227], off
	s_barrier
	s_waitcnt lgkmcnt(0)
	s_waitcnt lgkmcnt(0)
	v_mfma_f32_16x16x32_bf16 v[60:63], v[128:131], v[144:147], v[60:63]
	v_mfma_f32_16x16x32_bf16 v[56:59], v[136:139], v[144:147], v[56:59]
	v_mfma_f32_16x16x32_bf16 v[44:47], v[128:131], v[172:175], v[44:47]
	v_mfma_f32_16x16x32_bf16 v[40:43], v[136:139], v[172:175], v[40:43]
	v_mfma_f32_16x16x32_bf16 v[28:31], v[128:131], v[188:191], v[28:31]
	v_mfma_f32_16x16x32_bf16 v[24:27], v[136:139], v[188:191], v[24:27]
	v_mfma_f32_16x16x32_bf16 v[12:15], v[128:131], v[196:199], v[12:15]
	v_mfma_f32_16x16x32_bf16 v[8:11], v[136:139], v[196:199], v[8:11]
	v_mfma_f32_16x16x32_bf16 v[60:63], v[132:135], v[168:171], v[60:63]
	v_mfma_f32_16x16x32_bf16 v[56:59], v[140:143], v[168:171], v[56:59]
	v_mfma_f32_16x16x32_bf16 v[44:47], v[132:135], v[184:187], v[44:47]
	v_mfma_f32_16x16x32_bf16 v[40:43], v[140:143], v[184:187], v[40:43]
	v_mfma_f32_16x16x32_bf16 v[28:31], v[132:135], v[192:195], v[28:31]
	v_mfma_f32_16x16x32_bf16 v[24:27], v[140:143], v[192:195], v[24:27]
	v_mfma_f32_16x16x32_bf16 v[12:15], v[132:135], v[200:203], v[12:15]
	v_mfma_f32_16x16x32_bf16 v[8:11], v[140:143], v[200:203], v[8:11]
	s_barrier
	s_add_u32 s78, s6, 0x80000
	s_addc_u32 s79, s7, 0
	s_add_i32 s39, s81, s33
	v_lshl_add_u64 v[128:129], s[78:79], 0, v[150:151]
	s_mov_b32 m0, s39
	s_nop 0
	global_load_lds_dwordx4 v[128:129], off
	v_lshl_add_u64 v[128:129], s[78:79], 0, v[154:155]
	s_add_i32 m0, s39, 0x2000
	s_nop 0
	global_load_lds_dwordx4 v[128:129], off
	s_waitcnt vmcnt(6)
	s_barrier
	v_mfma_f32_16x16x32_bf16 v[52:55], v[204:207], v[144:147], v[52:55]
	v_mfma_f32_16x16x32_bf16 v[48:51], v[214:217], v[144:147], v[48:51]
	v_mfma_f32_16x16x32_bf16 v[36:39], v[204:207], v[172:175], v[36:39]
	v_mfma_f32_16x16x32_bf16 v[32:35], v[214:217], v[172:175], v[32:35]
	v_mfma_f32_16x16x32_bf16 v[20:23], v[204:207], v[188:191], v[20:23]
	v_mfma_f32_16x16x32_bf16 v[16:19], v[214:217], v[188:191], v[16:19]
	v_mfma_f32_16x16x32_bf16 v[4:7], v[204:207], v[196:199], v[4:7]
	v_mfma_f32_16x16x32_bf16 v[0:3], v[214:217], v[196:199], v[0:3]
	v_mfma_f32_16x16x32_bf16 v[52:55], v[210:213], v[168:171], v[52:55]
	v_mfma_f32_16x16x32_bf16 v[48:51], v[218:221], v[168:171], v[48:51]
	v_mfma_f32_16x16x32_bf16 v[36:39], v[210:213], v[184:187], v[36:39]
	v_mfma_f32_16x16x32_bf16 v[32:35], v[218:221], v[184:187], v[32:35]
	v_mfma_f32_16x16x32_bf16 v[20:23], v[210:213], v[192:195], v[20:23]
	v_mfma_f32_16x16x32_bf16 v[16:19], v[218:221], v[192:195], v[16:19]
	v_mfma_f32_16x16x32_bf16 v[4:7], v[210:213], v[200:203], v[4:7]
	v_mfma_f32_16x16x32_bf16 v[0:3], v[218:221], v[200:203], v[0:3]
	s_add_i32 s39, 0, 0x18000
	v_add_u32_e32 v140, s39, v180
	s_barrier
	ds_read_b128 v[128:131], v140
	ds_read_b128 v[132:135], v140 offset:1024
	ds_read_b128 v[136:139], v140 offset:2048
	ds_read_b128 v[140:143], v140 offset:3072
	s_add_u32 s8, s8, 0x80000
	s_addc_u32 s9, s9, 0
	s_mov_b32 m0, s51
	v_lshl_add_u64 v[204:205], s[8:9], 0, v[148:149]
	ds_read_b128 v[144:147], v182 offset:32768
	ds_read_b128 v[168:171], v182 offset:33792
	ds_read_b128 v[172:175], v182 offset:34816
	ds_read_b128 v[184:187], v182 offset:35840
	ds_read_b128 v[188:191], v182 offset:36864
	ds_read_b128 v[192:195], v182 offset:37888
	ds_read_b128 v[196:199], v182 offset:38912
	ds_read_b128 v[200:203], v182 offset:39936
	global_load_lds_dwordx4 v[204:205], off
	v_lshl_add_u64 v[204:205], s[8:9], 0, v[152:153]
	s_mov_b32 m0, s55
	s_nop 0
	global_load_lds_dwordx4 v[204:205], off
	s_waitcnt lgkmcnt(8)
	s_barrier
	s_waitcnt lgkmcnt(0)
	s_waitcnt lgkmcnt(0)
	v_mfma_f32_16x16x32_bf16 v[124:127], v[128:131], v[144:147], v[124:127]
	v_mfma_f32_16x16x32_bf16 v[120:123], v[136:139], v[144:147], v[120:123]
	v_mfma_f32_16x16x32_bf16 v[108:111], v[128:131], v[172:175], v[108:111]
	v_mfma_f32_16x16x32_bf16 v[104:107], v[136:139], v[172:175], v[104:107]
	v_mfma_f32_16x16x32_bf16 v[92:95], v[128:131], v[188:191], v[92:95]
	v_mfma_f32_16x16x32_bf16 v[88:91], v[136:139], v[188:191], v[88:91]
	v_mfma_f32_16x16x32_bf16 v[76:79], v[128:131], v[196:199], v[76:79]
	v_mfma_f32_16x16x32_bf16 v[72:75], v[136:139], v[196:199], v[72:75]
	v_mfma_f32_16x16x32_bf16 v[124:127], v[132:135], v[168:171], v[124:127]
	v_mfma_f32_16x16x32_bf16 v[120:123], v[140:143], v[168:171], v[120:123]
	v_mfma_f32_16x16x32_bf16 v[108:111], v[132:135], v[184:187], v[108:111]
	v_mfma_f32_16x16x32_bf16 v[104:107], v[140:143], v[184:187], v[104:107]
	v_mfma_f32_16x16x32_bf16 v[92:95], v[132:135], v[192:195], v[92:95]
	v_mfma_f32_16x16x32_bf16 v[88:91], v[140:143], v[192:195], v[88:91]
	v_mfma_f32_16x16x32_bf16 v[76:79], v[132:135], v[200:203], v[76:79]
	v_mfma_f32_16x16x32_bf16 v[72:75], v[140:143], v[200:203], v[72:75]
	s_barrier
	s_add_i32 s8, 0, 0x1c000
	s_add_i32 s9, s39, s33
	v_add_u32_e32 v156, s8, v180
	v_lshl_add_u64 v[176:177], v[176:177], 0, s[24:25]
	s_mov_b32 m0, s9
	ds_read_b128 v[204:207], v156
	ds_read_b128 v[210:213], v156 offset:1024
	ds_read_b128 v[214:217], v156 offset:2048
	ds_read_b128 v[218:221], v156 offset:3072
	global_load_lds_dwordx4 v[176:177], off
	v_lshl_add_u64 v[176:177], v[222:223], 0, s[24:25]
	s_add_i32 m0, s9, 0x2000
	s_nop 0
	global_load_lds_dwordx4 v[176:177], off
	s_barrier
	s_waitcnt lgkmcnt(0)
	s_waitcnt lgkmcnt(0)
	v_mfma_f32_16x16x32_bf16 v[116:119], v[204:207], v[144:147], v[116:119]
	v_mfma_f32_16x16x32_bf16 v[112:115], v[214:217], v[144:147], v[112:115]
	v_mfma_f32_16x16x32_bf16 v[100:103], v[204:207], v[172:175], v[100:103]
	v_mfma_f32_16x16x32_bf16 v[96:99], v[214:217], v[172:175], v[96:99]
	v_mfma_f32_16x16x32_bf16 v[84:87], v[204:207], v[188:191], v[84:87]
	v_mfma_f32_16x16x32_bf16 v[80:83], v[214:217], v[188:191], v[80:83]
	v_mfma_f32_16x16x32_bf16 v[68:71], v[204:207], v[196:199], v[68:71]
	v_mfma_f32_16x16x32_bf16 v[64:67], v[214:217], v[196:199], v[64:67]
	v_mfma_f32_16x16x32_bf16 v[116:119], v[210:213], v[168:171], v[116:119]
	v_mfma_f32_16x16x32_bf16 v[112:115], v[218:221], v[168:171], v[112:115]
	v_mfma_f32_16x16x32_bf16 v[100:103], v[210:213], v[184:187], v[100:103]
	v_mfma_f32_16x16x32_bf16 v[96:99], v[218:221], v[184:187], v[96:99]
	v_mfma_f32_16x16x32_bf16 v[84:87], v[210:213], v[192:195], v[84:87]
	v_mfma_f32_16x16x32_bf16 v[80:83], v[218:221], v[192:195], v[80:83]
	v_mfma_f32_16x16x32_bf16 v[68:71], v[210:213], v[200:203], v[68:71]
	v_mfma_f32_16x16x32_bf16 v[64:67], v[218:221], v[200:203], v[64:67]
	s_mov_b32 m0, s83
	v_lshl_add_u64 v[176:177], v[224:225], 0, s[24:25]
	s_barrier
	ds_read_b128 v[144:147], v182 offset:49152
	ds_read_b128 v[168:171], v182 offset:50176
	ds_read_b128 v[172:175], v182 offset:51200
	ds_read_b128 v[184:187], v182 offset:52224
	ds_read_b128 v[188:191], v182 offset:53248
	ds_read_b128 v[192:195], v182 offset:54272
	ds_read_b128 v[196:199], v182 offset:55296
	ds_read_b128 v[200:203], v182 offset:56320
	global_load_lds_dwordx4 v[176:177], off
	v_lshl_add_u64 v[176:177], v[226:227], 0, s[24:25]
	s_mov_b32 m0, s91
	s_nop 0
	global_load_lds_dwordx4 v[176:177], off
	s_barrier
	s_waitcnt lgkmcnt(0)
	s_waitcnt lgkmcnt(0)
	v_mfma_f32_16x16x32_bf16 v[60:63], v[128:131], v[144:147], v[60:63]
	v_mfma_f32_16x16x32_bf16 v[56:59], v[136:139], v[144:147], v[56:59]
	v_mfma_f32_16x16x32_bf16 v[44:47], v[128:131], v[172:175], v[44:47]
	v_mfma_f32_16x16x32_bf16 v[40:43], v[136:139], v[172:175], v[40:43]
	v_mfma_f32_16x16x32_bf16 v[28:31], v[128:131], v[188:191], v[28:31]
	v_mfma_f32_16x16x32_bf16 v[24:27], v[136:139], v[188:191], v[24:27]
	v_mfma_f32_16x16x32_bf16 v[12:15], v[128:131], v[196:199], v[12:15]
	v_mfma_f32_16x16x32_bf16 v[8:11], v[136:139], v[196:199], v[8:11]
	v_mfma_f32_16x16x32_bf16 v[60:63], v[132:135], v[168:171], v[60:63]
	v_mfma_f32_16x16x32_bf16 v[56:59], v[140:143], v[168:171], v[56:59]
	v_mfma_f32_16x16x32_bf16 v[44:47], v[132:135], v[184:187], v[44:47]
	v_mfma_f32_16x16x32_bf16 v[40:43], v[140:143], v[184:187], v[40:43]
	v_mfma_f32_16x16x32_bf16 v[28:31], v[132:135], v[192:195], v[28:31]
	v_mfma_f32_16x16x32_bf16 v[24:27], v[140:143], v[192:195], v[24:27]
	v_mfma_f32_16x16x32_bf16 v[12:15], v[132:135], v[200:203], v[12:15]
	v_mfma_f32_16x16x32_bf16 v[8:11], v[140:143], v[200:203], v[8:11]
	s_barrier
	s_add_u32 s6, s6, 0x80080
	s_addc_u32 s7, s7, 0
	s_add_i32 s8, s8, s33
	v_lshl_add_u64 v[128:129], s[6:7], 0, v[150:151]
	s_mov_b32 m0, s8
	s_nop 0
	global_load_lds_dwordx4 v[128:129], off
	v_lshl_add_u64 v[128:129], s[6:7], 0, v[154:155]
	s_add_i32 m0, s8, 0x2000
	s_nop 0
	global_load_lds_dwordx4 v[128:129], off
	s_waitcnt vmcnt(6)
	s_barrier
	v_mfma_f32_16x16x32_bf16 v[52:55], v[204:207], v[144:147], v[52:55]
	v_mfma_f32_16x16x32_bf16 v[48:51], v[214:217], v[144:147], v[48:51]
	v_mfma_f32_16x16x32_bf16 v[36:39], v[204:207], v[172:175], v[36:39]
	v_mfma_f32_16x16x32_bf16 v[32:35], v[214:217], v[172:175], v[32:35]
	v_mfma_f32_16x16x32_bf16 v[20:23], v[204:207], v[188:191], v[20:23]
	v_mfma_f32_16x16x32_bf16 v[16:19], v[214:217], v[188:191], v[16:19]
	v_mfma_f32_16x16x32_bf16 v[4:7], v[204:207], v[196:199], v[4:7]
	v_mfma_f32_16x16x32_bf16 v[0:3], v[214:217], v[196:199], v[0:3]
	v_mfma_f32_16x16x32_bf16 v[52:55], v[210:213], v[168:171], v[52:55]
	v_mfma_f32_16x16x32_bf16 v[48:51], v[218:221], v[168:171], v[48:51]
	v_mfma_f32_16x16x32_bf16 v[36:39], v[210:213], v[184:187], v[36:39]
	v_mfma_f32_16x16x32_bf16 v[32:35], v[218:221], v[184:187], v[32:35]
	v_mfma_f32_16x16x32_bf16 v[20:23], v[210:213], v[192:195], v[20:23]
	v_mfma_f32_16x16x32_bf16 v[16:19], v[218:221], v[192:195], v[16:19]
	v_mfma_f32_16x16x32_bf16 v[4:7], v[210:213], v[200:203], v[4:7]
	v_mfma_f32_16x16x32_bf16 v[0:3], v[218:221], v[200:203], v[0:3]
	s_add_i32 s37, s37, 2
	s_add_u32 s4, s4, 0x100
	s_addc_u32 s5, s5, 0
	s_add_u32 s35, s35, 0x100
	s_addc_u32 s36, s36, 0
	s_cmp_gt_u32 s37, 29
	s_barrier
	s_cbranch_scc0 .LBB0_262
	v_mov_b32_e32 v185, v179
	v_mov_b32_e32 v184, v178
	s_cmp_lt_i32 s90, 33
	s_mov_b64 s[4:5], -1
	s_cbranch_scc0 .LBB0_589
	s_cmp_gt_i32 s82, 3
	s_cbranch_scc0 .LBB0_586
	s_cmp_gt_u32 s82, 7
	s_cbranch_scc0 .LBB0_551
	s_cmp_gt_u32 s82, 15
	s_cbranch_scc0 .LBB0_548
	s_cmp_gt_u32 s82, 23
	s_cbranch_scc0 .LBB0_545
	s_cmp_gt_u32 s82, 27
	s_cbranch_scc0 .LBB0_486
	s_cmp_gt_u32 s82, 31
	s_cbranch_scc0 .LBB0_315
	s_cmp_gt_u32 s82, 35
	s_cbranch_scc0 .LBB0_280
	s_cmp_gt_u32 s82, 39
	s_cbranch_scc0 .LBB0_277
	s_lshl_b32 s4, s90, 8
	s_add_i32 s4, s4, s57
	v_lshl_add_u32 v128, v185, 3, s59
	v_add_u32_e32 v132, s4, v184
	v_ashrrev_i32_e32 v129, 31, v128
	v_mad_i64_i32 v[130:131], s[4:5], v132, s28, 0
	s_cmp_gt_u32 s82, 41
	s_mov_b64 s[4:5], -1
	v_lshl_add_u64 v[130:131], s[0:1], 0, v[130:131]
	v_lshlrev_b64 v[128:129], 1, v[128:129]
	v_add_u32_e32 v138, 16, v132
	v_add_u32_e32 v137, 32, v132
	v_add_u32_e32 v136, 48, v132
	v_add_u32_e32 v135, 0x80, v132
	v_add_u32_e32 v134, 0x90, v132
	v_add_u32_e32 v133, 0xa0, v132
	v_add_u32_e32 v132, 0xb0, v132
	s_cbranch_scc0 .LBB0_274
	s_lshl_b32 s20, s82, 8
	s_lshl_b64 s[4:5], s[20:21], 1
	v_lshl_add_u64 v[144:145], v[130:131], 0, s[4:5]
	v_cvt_pk_bf16_f32 v140, v124, v125
	v_cvt_pk_bf16_f32 v141, v126, v127
	v_cvt_pk_bf16_f32 v142, v120, v121
	v_cvt_pk_bf16_f32 v143, v122, v123
	v_lshl_add_u64 v[144:145], v[144:145], 0, v[128:129]
	global_store_dwordx4 v[144:145], v[140:143], off
	s_nop 1
	v_cvt_pk_bf16_f32 v140, v116, v117
	v_cvt_pk_bf16_f32 v141, v118, v119
	v_cvt_pk_bf16_f32 v142, v112, v113
	v_cvt_pk_bf16_f32 v143, v114, v115
	global_store_dwordx4 v[144:145], v[140:143], off offset:256
	v_mov_b64_e32 v[144:145], s[0:1]
	v_mad_i64_i32 v[146:147], s[6:7], v138, s28, v[144:145]
	v_lshl_add_u64 v[146:147], v[146:147], 0, s[4:5]
	v_cvt_pk_bf16_f32 v140, v108, v109
	v_cvt_pk_bf16_f32 v141, v110, v111
	v_cvt_pk_bf16_f32 v142, v104, v105
	v_cvt_pk_bf16_f32 v143, v106, v107
	v_lshl_add_u64 v[146:147], v[146:147], 0, v[128:129]
	global_store_dwordx4 v[146:147], v[140:143], off
	s_nop 1
	v_cvt_pk_bf16_f32 v140, v100, v101
	v_cvt_pk_bf16_f32 v141, v102, v103
	v_cvt_pk_bf16_f32 v142, v96, v97
	v_cvt_pk_bf16_f32 v143, v98, v99
	global_store_dwordx4 v[146:147], v[140:143], off offset:256
	v_mad_i64_i32 v[146:147], s[6:7], v137, s28, v[144:145]
	v_lshl_add_u64 v[146:147], v[146:147], 0, s[4:5]
	v_cvt_pk_bf16_f32 v140, v92, v93
	v_cvt_pk_bf16_f32 v141, v94, v95
	v_cvt_pk_bf16_f32 v142, v88, v89
	v_cvt_pk_bf16_f32 v143, v90, v91
	v_lshl_add_u64 v[146:147], v[146:147], 0, v[128:129]
	global_store_dwordx4 v[146:147], v[140:143], off
	s_nop 1
	v_cvt_pk_bf16_f32 v140, v84, v85
	v_cvt_pk_bf16_f32 v141, v86, v87
	v_cvt_pk_bf16_f32 v142, v80, v81
	v_cvt_pk_bf16_f32 v143, v82, v83
	global_store_dwordx4 v[146:147], v[140:143], off offset:256
	v_mad_i64_i32 v[146:147], s[6:7], v136, s28, v[144:145]
	v_lshl_add_u64 v[146:147], v[146:147], 0, s[4:5]
	v_cvt_pk_bf16_f32 v140, v76, v77
	v_cvt_pk_bf16_f32 v141, v78, v79
	v_cvt_pk_bf16_f32 v142, v72, v73
	v_cvt_pk_bf16_f32 v143, v74, v75
	v_lshl_add_u64 v[146:147], v[146:147], 0, v[128:129]
	global_store_dwordx4 v[146:147], v[140:143], off
	s_nop 1
	v_cvt_pk_bf16_f32 v140, v68, v69
	v_cvt_pk_bf16_f32 v141, v70, v71
	v_cvt_pk_bf16_f32 v142, v64, v65
	v_cvt_pk_bf16_f32 v143, v66, v67
	global_store_dwordx4 v[146:147], v[140:143], off offset:256
	v_mad_i64_i32 v[146:147], s[6:7], v135, s28, v[144:145]
	v_lshl_add_u64 v[146:147], v[146:147], 0, s[4:5]
	v_cvt_pk_bf16_f32 v140, v60, v61
	v_cvt_pk_bf16_f32 v141, v62, v63
	v_cvt_pk_bf16_f32 v142, v56, v57
	v_cvt_pk_bf16_f32 v143, v58, v59
	v_lshl_add_u64 v[146:147], v[146:147], 0, v[128:129]
	global_store_dwordx4 v[146:147], v[140:143], off
	s_nop 1
	v_cvt_pk_bf16_f32 v140, v52, v53
	v_cvt_pk_bf16_f32 v141, v54, v55
	v_cvt_pk_bf16_f32 v142, v48, v49
	v_cvt_pk_bf16_f32 v143, v50, v51
	global_store_dwordx4 v[146:147], v[140:143], off offset:256
	v_mad_i64_i32 v[146:147], s[6:7], v134, s28, v[144:145]
	v_lshl_add_u64 v[146:147], v[146:147], 0, s[4:5]
	v_cvt_pk_bf16_f32 v140, v44, v45
	v_cvt_pk_bf16_f32 v141, v46, v47
	v_cvt_pk_bf16_f32 v142, v40, v41
	v_cvt_pk_bf16_f32 v143, v42, v43
	v_lshl_add_u64 v[146:147], v[146:147], 0, v[128:129]
	global_store_dwordx4 v[146:147], v[140:143], off
	s_nop 1
	v_cvt_pk_bf16_f32 v140, v36, v37
	v_cvt_pk_bf16_f32 v141, v38, v39
	v_cvt_pk_bf16_f32 v142, v32, v33
	v_cvt_pk_bf16_f32 v143, v34, v35
	global_store_dwordx4 v[146:147], v[140:143], off offset:256
	v_mad_i64_i32 v[146:147], s[6:7], v133, s28, v[144:145]
	v_lshl_add_u64 v[146:147], v[146:147], 0, s[4:5]
	v_cvt_pk_bf16_f32 v140, v28, v29
	v_cvt_pk_bf16_f32 v141, v30, v31
	v_cvt_pk_bf16_f32 v142, v24, v25
	v_cvt_pk_bf16_f32 v143, v26, v27
	v_lshl_add_u64 v[146:147], v[146:147], 0, v[128:129]
	v_mad_i64_i32 v[144:145], s[6:7], v132, s28, v[144:145]
	global_store_dwordx4 v[146:147], v[140:143], off
	v_lshl_add_u64 v[144:145], v[144:145], 0, s[4:5]
	v_lshl_add_u64 v[144:145], v[144:145], 0, v[128:129]
	v_cvt_pk_bf16_f32 v140, v20, v21
	v_cvt_pk_bf16_f32 v141, v22, v23
	v_cvt_pk_bf16_f32 v142, v16, v17
	v_cvt_pk_bf16_f32 v143, v18, v19
	global_store_dwordx4 v[146:147], v[140:143], off offset:256
	s_mov_b64 s[4:5], 0
	s_nop 0
	v_cvt_pk_bf16_f32 v140, v12, v13
	v_cvt_pk_bf16_f32 v141, v14, v15
	v_cvt_pk_bf16_f32 v142, v8, v9
	v_cvt_pk_bf16_f32 v143, v10, v11
	global_store_dwordx4 v[144:145], v[140:143], off
	s_nop 1
	v_cvt_pk_bf16_f32 v140, v4, v5
	v_cvt_pk_bf16_f32 v141, v6, v7
	v_cvt_pk_bf16_f32 v142, v0, v1
	v_cvt_pk_bf16_f32 v143, v2, v3
	global_store_dwordx4 v[144:145], v[140:143], off offset:256

.LBB0_974:
	ds_read_b128 v[150:153], v147
	ds_read_b128 v[154:157], v147 offset:1024
	ds_read_b128 v[158:161], v147 offset:2048
	ds_read_b128 v[162:165], v147 offset:3072
	s_add_u32 s16, s14, 0x100
	s_addc_u32 s17, s15, 0
	s_cmp_eq_u32 s44, 52
	s_cselect_b32 s21, s3, s17
	s_cselect_b32 s20, s2, s16
	s_cselect_b32 s19, s5, s43
	s_cselect_b32 s18, s4, s42
	v_lshl_add_u64 v[198:199], s[14:15], 0, v[136:137]
	s_add_i32 m0, s24, 0xc000
	ds_read_b128 v[166:169], v148
	ds_read_b128 v[170:173], v148 offset:1024
	ds_read_b128 v[174:177], v148 offset:2048
	ds_read_b128 v[178:181], v148 offset:3072
	ds_read_b128 v[182:185], v148 offset:4096
	ds_read_b128 v[186:189], v148 offset:5120
	ds_read_b128 v[190:193], v148 offset:6144
	ds_read_b128 v[194:197], v148 offset:7168
	global_load_lds_dwordx4 v[198:199], off
	v_lshl_add_u64 v[198:199], s[14:15], 0, v[138:139]
	s_add_i32 m0, s24, 0xe000
	s_nop 0
	global_load_lds_dwordx4 v[198:199], off
	s_waitcnt lgkmcnt(8)
	s_barrier
	s_waitcnt lgkmcnt(0)
	s_waitcnt lgkmcnt(0)
	v_mfma_f32_16x16x32_bf16 v[124:127], v[150:153], v[166:169], v[124:127]
	v_mfma_f32_16x16x32_bf16 v[120:123], v[158:161], v[166:169], v[120:123]
	v_mfma_f32_16x16x32_bf16 v[116:119], v[150:153], v[174:177], v[116:119]
	v_mfma_f32_16x16x32_bf16 v[112:115], v[158:161], v[174:177], v[112:115]
	v_mfma_f32_16x16x32_bf16 v[100:103], v[150:153], v[182:185], v[100:103]
	v_mfma_f32_16x16x32_bf16 v[96:99], v[158:161], v[182:185], v[96:99]
	v_mfma_f32_16x16x32_bf16 v[84:87], v[150:153], v[190:193], v[84:87]
	v_mfma_f32_16x16x32_bf16 v[80:83], v[158:161], v[190:193], v[80:83]
	v_mfma_f32_16x16x32_bf16 v[124:127], v[154:157], v[170:173], v[124:127]
	v_mfma_f32_16x16x32_bf16 v[120:123], v[162:165], v[170:173], v[120:123]
	v_mfma_f32_16x16x32_bf16 v[116:119], v[154:157], v[178:181], v[116:119]
	v_mfma_f32_16x16x32_bf16 v[112:115], v[162:165], v[178:181], v[112:115]
	v_mfma_f32_16x16x32_bf16 v[100:103], v[154:157], v[186:189], v[100:103]
	v_mfma_f32_16x16x32_bf16 v[96:99], v[162:165], v[186:189], v[96:99]
	v_mfma_f32_16x16x32_bf16 v[84:87], v[154:157], v[194:197], v[84:87]
	v_mfma_f32_16x16x32_bf16 v[80:83], v[162:165], v[194:197], v[80:83]
	s_barrier
	s_add_i32 s14, s35, s23
	v_lshl_add_u64 v[206:207], s[18:19], 0, v[130:131]
	s_mov_b32 m0, s14
	ds_read_b128 v[198:201], v149
	ds_read_b128 v[202:205], v149 offset:1024
	ds_read_b128 v[210:213], v149 offset:2048
	ds_read_b128 v[214:217], v149 offset:3072
	global_load_lds_dwordx4 v[206:207], off
	v_lshl_add_u64 v[218:219], s[18:19], 0, v[134:135]
	s_add_i32 m0, s14, 0x2000
	s_nop 0
	global_load_lds_dwordx4 v[218:219], off
	s_barrier
	s_waitcnt lgkmcnt(0)
	s_waitcnt lgkmcnt(0)
	v_mfma_f32_16x16x32_bf16 v[108:111], v[198:201], v[166:169], v[108:111]
	v_mfma_f32_16x16x32_bf16 v[104:107], v[210:213], v[166:169], v[104:107]
	v_mfma_f32_16x16x32_bf16 v[92:95], v[198:201], v[174:177], v[92:95]
	v_mfma_f32_16x16x32_bf16 v[88:91], v[210:213], v[174:177], v[88:91]
	v_mfma_f32_16x16x32_bf16 v[76:79], v[198:201], v[182:185], v[76:79]
	v_mfma_f32_16x16x32_bf16 v[72:75], v[210:213], v[182:185], v[72:75]
	v_mfma_f32_16x16x32_bf16 v[68:71], v[198:201], v[190:193], v[68:71]
	v_mfma_f32_16x16x32_bf16 v[64:67], v[210:213], v[190:193], v[64:67]
	v_mfma_f32_16x16x32_bf16 v[108:111], v[202:205], v[170:173], v[108:111]
	v_mfma_f32_16x16x32_bf16 v[104:107], v[214:217], v[170:173], v[104:107]
	v_mfma_f32_16x16x32_bf16 v[92:95], v[202:205], v[178:181], v[92:95]
	v_mfma_f32_16x16x32_bf16 v[88:91], v[214:217], v[178:181], v[88:91]
	v_mfma_f32_16x16x32_bf16 v[76:79], v[202:205], v[186:189], v[76:79]
	v_mfma_f32_16x16x32_bf16 v[72:75], v[214:217], v[186:189], v[72:75]
	v_mfma_f32_16x16x32_bf16 v[68:71], v[202:205], v[194:197], v[68:71]
	v_mfma_f32_16x16x32_bf16 v[64:67], v[214:217], v[194:197], v[64:67]
	s_mov_b32 m0, s24
	v_lshl_add_u64 v[220:221], s[20:21], 0, v[128:129]
	s_barrier
	ds_read_b128 v[166:169], v148 offset:16384
	ds_read_b128 v[170:173], v148 offset:17408
	ds_read_b128 v[174:177], v148 offset:18432
	ds_read_b128 v[178:181], v148 offset:19456
	ds_read_b128 v[182:185], v148 offset:20480
	ds_read_b128 v[186:189], v148 offset:21504
	ds_read_b128 v[190:193], v148 offset:22528
	ds_read_b128 v[194:197], v148 offset:23552
	global_load_lds_dwordx4 v[220:221], off
	v_lshl_add_u64 v[222:223], s[20:21], 0, v[132:133]
	s_mov_b32 m0, s25
	s_nop 0
	global_load_lds_dwordx4 v[222:223], off
	s_barrier
	s_waitcnt lgkmcnt(0)
	s_waitcnt lgkmcnt(0)
	v_mfma_f32_16x16x32_bf16 v[60:63], v[150:153], v[166:169], v[60:63]
	v_mfma_f32_16x16x32_bf16 v[56:59], v[158:161], v[166:169], v[56:59]
	v_mfma_f32_16x16x32_bf16 v[52:55], v[150:153], v[174:177], v[52:55]
	v_mfma_f32_16x16x32_bf16 v[48:51], v[158:161], v[174:177], v[48:51]
	v_mfma_f32_16x16x32_bf16 v[36:39], v[150:153], v[182:185], v[36:39]
	v_mfma_f32_16x16x32_bf16 v[32:35], v[158:161], v[182:185], v[32:35]
	v_mfma_f32_16x16x32_bf16 v[20:23], v[150:153], v[190:193], v[20:23]
	v_mfma_f32_16x16x32_bf16 v[16:19], v[158:161], v[190:193], v[16:19]
	v_mfma_f32_16x16x32_bf16 v[60:63], v[154:157], v[170:173], v[60:63]
	v_mfma_f32_16x16x32_bf16 v[56:59], v[162:165], v[170:173], v[56:59]
	v_mfma_f32_16x16x32_bf16 v[52:55], v[154:157], v[178:181], v[52:55]
	v_mfma_f32_16x16x32_bf16 v[48:51], v[162:165], v[178:181], v[48:51]
	v_mfma_f32_16x16x32_bf16 v[36:39], v[154:157], v[186:189], v[36:39]
	v_mfma_f32_16x16x32_bf16 v[32:35], v[162:165], v[186:189], v[32:35]
	v_mfma_f32_16x16x32_bf16 v[20:23], v[154:157], v[194:197], v[20:23]
	v_mfma_f32_16x16x32_bf16 v[16:19], v[162:165], v[194:197], v[16:19]
	s_barrier
	s_add_u32 s14, s18, 0xe0000
	s_addc_u32 s15, s19, 0
	s_add_i32 s45, s36, s23
	v_lshl_add_u64 v[150:151], s[14:15], 0, v[130:131]
	s_mov_b32 m0, s45
	s_nop 0
	global_load_lds_dwordx4 v[150:151], off
	v_lshl_add_u64 v[150:151], s[14:15], 0, v[134:135]
	s_add_i32 m0, s45, 0x2000
	s_nop 0
	global_load_lds_dwordx4 v[150:151], off
	s_waitcnt vmcnt(6)
	s_barrier
	v_mfma_f32_16x16x32_bf16 v[44:47], v[198:201], v[166:169], v[44:47]
	v_mfma_f32_16x16x32_bf16 v[40:43], v[210:213], v[166:169], v[40:43]
	v_mfma_f32_16x16x32_bf16 v[28:31], v[198:201], v[174:177], v[28:31]
	v_mfma_f32_16x16x32_bf16 v[24:27], v[210:213], v[174:177], v[24:27]
	v_mfma_f32_16x16x32_bf16 v[12:15], v[198:201], v[182:185], v[12:15]
	v_mfma_f32_16x16x32_bf16 v[8:11], v[210:213], v[182:185], v[8:11]
	v_mfma_f32_16x16x32_bf16 v[4:7], v[198:201], v[190:193], v[4:7]
	v_mfma_f32_16x16x32_bf16 v[0:3], v[210:213], v[190:193], v[0:3]
	v_mfma_f32_16x16x32_bf16 v[44:47], v[202:205], v[170:173], v[44:47]
	v_mfma_f32_16x16x32_bf16 v[40:43], v[214:217], v[170:173], v[40:43]
	v_mfma_f32_16x16x32_bf16 v[28:31], v[202:205], v[178:181], v[28:31]
	v_mfma_f32_16x16x32_bf16 v[24:27], v[214:217], v[178:181], v[24:27]
	v_mfma_f32_16x16x32_bf16 v[12:15], v[202:205], v[186:189], v[12:15]
	v_mfma_f32_16x16x32_bf16 v[8:11], v[214:217], v[186:189], v[8:11]
	v_mfma_f32_16x16x32_bf16 v[4:7], v[202:205], v[194:197], v[4:7]
	v_mfma_f32_16x16x32_bf16 v[0:3], v[214:217], v[194:197], v[0:3]
	s_add_i32 s45, 0, 0x18000
	v_add_u32_e32 v162, s45, v146
	s_barrier
	ds_read_b128 v[150:153], v162
	ds_read_b128 v[154:157], v162 offset:1024
	ds_read_b128 v[158:161], v162 offset:2048
	ds_read_b128 v[162:165], v162 offset:3072
	s_add_u32 s14, s20, 0xe0000
	s_addc_u32 s15, s21, 0
	s_mov_b32 m0, s26
	v_lshl_add_u64 v[198:199], s[14:15], 0, v[128:129]
	ds_read_b128 v[166:169], v148 offset:32768
	ds_read_b128 v[170:173], v148 offset:33792
	ds_read_b128 v[174:177], v148 offset:34816
	ds_read_b128 v[178:181], v148 offset:35840
	ds_read_b128 v[182:185], v148 offset:36864
	ds_read_b128 v[186:189], v148 offset:37888
	ds_read_b128 v[190:193], v148 offset:38912
	ds_read_b128 v[194:197], v148 offset:39936
	global_load_lds_dwordx4 v[198:199], off
	v_lshl_add_u64 v[198:199], s[14:15], 0, v[132:133]
	s_mov_b32 m0, s27
	s_nop 0
	global_load_lds_dwordx4 v[198:199], off
	s_waitcnt lgkmcnt(8)
	s_barrier
	s_waitcnt lgkmcnt(0)
	s_waitcnt lgkmcnt(0)
	v_mfma_f32_16x16x32_bf16 v[124:127], v[150:153], v[166:169], v[124:127]
	v_mfma_f32_16x16x32_bf16 v[120:123], v[158:161], v[166:169], v[120:123]
	v_mfma_f32_16x16x32_bf16 v[116:119], v[150:153], v[174:177], v[116:119]
	v_mfma_f32_16x16x32_bf16 v[112:115], v[158:161], v[174:177], v[112:115]
	v_mfma_f32_16x16x32_bf16 v[100:103], v[150:153], v[182:185], v[100:103]
	v_mfma_f32_16x16x32_bf16 v[96:99], v[158:161], v[182:185], v[96:99]
	v_mfma_f32_16x16x32_bf16 v[84:87], v[150:153], v[190:193], v[84:87]
	v_mfma_f32_16x16x32_bf16 v[80:83], v[158:161], v[190:193], v[80:83]
	v_mfma_f32_16x16x32_bf16 v[124:127], v[154:157], v[170:173], v[124:127]
	v_mfma_f32_16x16x32_bf16 v[120:123], v[162:165], v[170:173], v[120:123]
	v_mfma_f32_16x16x32_bf16 v[116:119], v[154:157], v[178:181], v[116:119]
	v_mfma_f32_16x16x32_bf16 v[112:115], v[162:165], v[178:181], v[112:115]
	v_mfma_f32_16x16x32_bf16 v[100:103], v[154:157], v[186:189], v[100:103]
	v_mfma_f32_16x16x32_bf16 v[96:99], v[162:165], v[186:189], v[96:99]
	v_mfma_f32_16x16x32_bf16 v[84:87], v[154:157], v[194:197], v[84:87]
	v_mfma_f32_16x16x32_bf16 v[80:83], v[162:165], v[194:197], v[80:83]
	s_barrier
	s_add_i32 s20, 0, 0x1c000
	s_add_i32 s14, s45, s23
	v_add_u32_e32 v214, s20, v146
	v_lshl_add_u64 v[206:207], v[206:207], 0, s[8:9]
	s_mov_b32 m0, s14
	ds_read_b128 v[198:201], v214
	ds_read_b128 v[202:205], v214 offset:1024
	ds_read_b128 v[210:213], v214 offset:2048
	ds_read_b128 v[214:217], v214 offset:3072
	global_load_lds_dwordx4 v[206:207], off
	v_lshl_add_u64 v[206:207], v[218:219], 0, s[8:9]
	s_add_i32 m0, s14, 0x2000
	s_nop 0
	global_load_lds_dwordx4 v[206:207], off
	s_barrier
	s_waitcnt lgkmcnt(0)
	s_waitcnt lgkmcnt(0)
	v_mfma_f32_16x16x32_bf16 v[108:111], v[198:201], v[166:169], v[108:111]
	v_mfma_f32_16x16x32_bf16 v[104:107], v[210:213], v[166:169], v[104:107]
	v_mfma_f32_16x16x32_bf16 v[92:95], v[198:201], v[174:177], v[92:95]
	v_mfma_f32_16x16x32_bf16 v[88:91], v[210:213], v[174:177], v[88:91]
	v_mfma_f32_16x16x32_bf16 v[76:79], v[198:201], v[182:185], v[76:79]
	v_mfma_f32_16x16x32_bf16 v[72:75], v[210:213], v[182:185], v[72:75]
	v_mfma_f32_16x16x32_bf16 v[68:71], v[198:201], v[190:193], v[68:71]
	v_mfma_f32_16x16x32_bf16 v[64:67], v[210:213], v[190:193], v[64:67]
	v_mfma_f32_16x16x32_bf16 v[108:111], v[202:205], v[170:173], v[108:111]
	v_mfma_f32_16x16x32_bf16 v[104:107], v[214:217], v[170:173], v[104:107]
	v_mfma_f32_16x16x32_bf16 v[92:95], v[202:205], v[178:181], v[92:95]
	v_mfma_f32_16x16x32_bf16 v[88:91], v[214:217], v[178:181], v[88:91]
	v_mfma_f32_16x16x32_bf16 v[76:79], v[202:205], v[186:189], v[76:79]
	v_mfma_f32_16x16x32_bf16 v[72:75], v[214:217], v[186:189], v[72:75]
	v_mfma_f32_16x16x32_bf16 v[68:71], v[202:205], v[194:197], v[68:71]
	v_mfma_f32_16x16x32_bf16 v[64:67], v[214:217], v[194:197], v[64:67]
	s_mov_b32 m0, s31
	v_lshl_add_u64 v[206:207], v[220:221], 0, s[8:9]
	s_barrier
	ds_read_b128 v[166:169], v148 offset:49152
	ds_read_b128 v[170:173], v148 offset:50176
	ds_read_b128 v[174:177], v148 offset:51200
	ds_read_b128 v[178:181], v148 offset:52224
	ds_read_b128 v[182:185], v148 offset:53248
	ds_read_b128 v[186:189], v148 offset:54272
	ds_read_b128 v[190:193], v148 offset:55296
	ds_read_b128 v[194:197], v148 offset:56320
	global_load_lds_dwordx4 v[206:207], off
	v_lshl_add_u64 v[206:207], v[222:223], 0, s[8:9]
	s_mov_b32 m0, s33
	s_nop 0
	global_load_lds_dwordx4 v[206:207], off
	s_barrier
	s_waitcnt lgkmcnt(0)
	s_waitcnt lgkmcnt(0)
	v_mfma_f32_16x16x32_bf16 v[60:63], v[150:153], v[166:169], v[60:63]
	v_mfma_f32_16x16x32_bf16 v[56:59], v[158:161], v[166:169], v[56:59]
	v_mfma_f32_16x16x32_bf16 v[52:55], v[150:153], v[174:177], v[52:55]
	v_mfma_f32_16x16x32_bf16 v[48:51], v[158:161], v[174:177], v[48:51]
	v_mfma_f32_16x16x32_bf16 v[36:39], v[150:153], v[182:185], v[36:39]
	v_mfma_f32_16x16x32_bf16 v[32:35], v[158:161], v[182:185], v[32:35]
	v_mfma_f32_16x16x32_bf16 v[20:23], v[150:153], v[190:193], v[20:23]
	v_mfma_f32_16x16x32_bf16 v[16:19], v[158:161], v[190:193], v[16:19]
	v_mfma_f32_16x16x32_bf16 v[60:63], v[154:157], v[170:173], v[60:63]
	v_mfma_f32_16x16x32_bf16 v[56:59], v[162:165], v[170:173], v[56:59]
	v_mfma_f32_16x16x32_bf16 v[52:55], v[154:157], v[178:181], v[52:55]
	v_mfma_f32_16x16x32_bf16 v[48:51], v[162:165], v[178:181], v[48:51]
	v_mfma_f32_16x16x32_bf16 v[36:39], v[154:157], v[186:189], v[36:39]
	v_mfma_f32_16x16x32_bf16 v[32:35], v[162:165], v[186:189], v[32:35]
	v_mfma_f32_16x16x32_bf16 v[20:23], v[154:157], v[194:197], v[20:23]
	v_mfma_f32_16x16x32_bf16 v[16:19], v[162:165], v[194:197], v[16:19]
	s_barrier
	s_add_u32 s14, s18, 0xe0080
	s_addc_u32 s15, s19, 0
	s_add_i32 s18, s20, s23
	v_lshl_add_u64 v[150:151], s[14:15], 0, v[130:131]
	s_mov_b32 m0, s18
	s_nop 0
	global_load_lds_dwordx4 v[150:151], off
	v_lshl_add_u64 v[150:151], s[14:15], 0, v[134:135]
	s_add_i32 m0, s18, 0x2000
	s_nop 0
	global_load_lds_dwordx4 v[150:151], off
	s_waitcnt vmcnt(6)
	s_barrier
	v_mfma_f32_16x16x32_bf16 v[44:47], v[198:201], v[166:169], v[44:47]
	v_mfma_f32_16x16x32_bf16 v[40:43], v[210:213], v[166:169], v[40:43]
	v_mfma_f32_16x16x32_bf16 v[28:31], v[198:201], v[174:177], v[28:31]
	v_mfma_f32_16x16x32_bf16 v[24:27], v[210:213], v[174:177], v[24:27]
	v_mfma_f32_16x16x32_bf16 v[12:15], v[198:201], v[182:185], v[12:15]
	v_mfma_f32_16x16x32_bf16 v[8:11], v[210:213], v[182:185], v[8:11]
	v_mfma_f32_16x16x32_bf16 v[4:7], v[198:201], v[190:193], v[4:7]
	v_mfma_f32_16x16x32_bf16 v[0:3], v[210:213], v[190:193], v[0:3]
	v_mfma_f32_16x16x32_bf16 v[44:47], v[202:205], v[170:173], v[44:47]
	v_mfma_f32_16x16x32_bf16 v[40:43], v[214:217], v[170:173], v[40:43]
	v_mfma_f32_16x16x32_bf16 v[28:31], v[202:205], v[178:181], v[28:31]
	v_mfma_f32_16x16x32_bf16 v[24:27], v[214:217], v[178:181], v[24:27]
	v_mfma_f32_16x16x32_bf16 v[12:15], v[202:205], v[186:189], v[12:15]
	v_mfma_f32_16x16x32_bf16 v[8:11], v[214:217], v[186:189], v[8:11]
	v_mfma_f32_16x16x32_bf16 v[4:7], v[202:205], v[194:197], v[4:7]
	v_mfma_f32_16x16x32_bf16 v[0:3], v[214:217], v[194:197], v[0:3]
	s_add_i32 s44, s44, 2
	s_add_u32 s42, s42, 0x100
	s_addc_u32 s43, s43, 0
	s_cmp_gt_u32 s44, 53
	s_mov_b64 s[14:15], s[16:17]
	s_barrier
	s_cbranch_scc0 .LBB0_974
	v_mov_b32_e32 v150, v145
	v_mov_b32_e32 v151, v144
	s_lshl_b32 s14, s34, 8
	s_add_i32 s14, s14, s29
	v_add_u32_e32 v150, s14, v150
	s_lshl_b32 s14, s41, 8
	s_or_b32 s14, s14, s30
	v_lshl_add_u32 v152, v151, 3, s14
	v_ashrrev_i32_e32 v151, 31, v150
	v_lshlrev_b64 v[150:151], 12, v[150:151]
	v_ashrrev_i32_e32 v153, 31, v152
	v_lshl_add_u64 v[150:151], s[10:11], 0, v[150:151]
	v_lshl_add_u64 v[150:151], v[152:153], 1, v[150:151]
	v_cvt_pk_bf16_f32 v108, v108, v109
	v_cvt_pk_bf16_f32 v109, v110, v111
	v_cvt_pk_bf16_f32 v110, v104, v105
	v_cvt_pk_bf16_f32 v111, v106, v107
	s_mov_b64 s[14:15], 0x10000
	global_store_dwordx4 v[150:151], v[108:111], off offset:256
	v_cvt_pk_bf16_f32 v92, v92, v93
	v_cvt_pk_bf16_f32 v93, v94, v95
	v_lshl_add_u64 v[108:109], v[150:151], 0, s[14:15]
	s_mov_b32 s14, 0x10000
	v_add_co_u32_e32 v110, vcc, s14, v150
	v_cvt_pk_bf16_f32 v94, v88, v89
	v_cvt_pk_bf16_f32 v95, v90, v91
	s_mov_b64 s[14:15], 0x20000
	v_addc_co_u32_e32 v111, vcc, 0, v151, vcc
	global_store_dwordx4 v[108:109], v[92:95], off offset:256
	v_cvt_pk_bf16_f32 v76, v76, v77
	v_cvt_pk_bf16_f32 v77, v78, v79
	v_lshl_add_u64 v[92:93], v[150:151], 0, s[14:15]
	s_mov_b32 s14, 0x20000
	v_add_co_u32_e32 v94, vcc, s14, v150
	v_cvt_pk_bf16_f32 v78, v72, v73
	v_cvt_pk_bf16_f32 v79, v74, v75
	s_mov_b64 s[14:15], 0x30000
	v_addc_co_u32_e32 v95, vcc, 0, v151, vcc
	global_store_dwordx4 v[92:93], v[76:79], off offset:256
	v_cvt_pk_bf16_f32 v68, v68, v69
	v_cvt_pk_bf16_f32 v69, v70, v71
	v_lshl_add_u64 v[76:77], v[150:151], 0, s[14:15]
	s_mov_b32 s14, 0x30000
	v_add_co_u32_e32 v78, vcc, s14, v150
	s_mov_b64 s[14:15], 0x80000
	s_nop 0
	v_addc_co_u32_e32 v79, vcc, 0, v151, vcc
	v_cvt_pk_bf16_f32 v70, v64, v65
	v_lshl_add_u64 v[64:65], v[150:151], 0, s[14:15]
	s_mov_b32 s14, 0x80000
	v_cvt_pk_bf16_f32 v60, v60, v61
	v_cvt_pk_bf16_f32 v61, v62, v63
	v_cvt_pk_bf16_f32 v62, v56, v57
	v_add_co_u32_e32 v56, vcc, s14, v150
	v_cvt_pk_bf16_f32 v44, v44, v45
	v_cvt_pk_bf16_f32 v45, v46, v47
	v_cvt_pk_bf16_f32 v46, v40, v41
	v_cvt_pk_bf16_f32 v47, v42, v43
	s_mov_b64 s[14:15], 0x90000
	v_addc_co_u32_e32 v57, vcc, 0, v151, vcc
	global_store_dwordx4 v[64:65], v[44:47], off offset:256
	v_cvt_pk_bf16_f32 v28, v28, v29
	v_cvt_pk_bf16_f32 v29, v30, v31
	v_lshl_add_u64 v[44:45], v[150:151], 0, s[14:15]
	s_mov_b32 s14, 0x90000
	v_add_co_u32_e32 v46, vcc, s14, v150
	v_cvt_pk_bf16_f32 v30, v24, v25
	s_nop 0
	v_addc_co_u32_e32 v47, vcc, 0, v151, vcc
	v_cvt_pk_bf16_f32 v31, v26, v27
	global_store_dwordx4 v[44:45], v[28:31], off offset:256
	s_mov_b64 s[14:15], 0xa0000
	v_cvt_pk_bf16_f32 v12, v12, v13
	v_add_co_u32_e32 v30, vcc, s37, v150
	v_lshl_add_u64 v[28:29], v[150:151], 0, s[14:15]
	s_nop 0
	v_addc_co_u32_e32 v31, vcc, 0, v151, vcc
	v_cvt_pk_bf16_f32 v13, v14, v15
	v_cvt_pk_bf16_f32 v14, v8, v9
	v_cvt_pk_bf16_f32 v15, v10, v11
	global_store_dwordx4 v[28:29], v[12:15], off offset:256
	v_cvt_pk_bf16_f32 v124, v124, v125
	v_cvt_pk_bf16_f32 v125, v126, v127
	v_add_co_u32_e32 v14, vcc, s38, v150
	v_cvt_pk_bf16_f32 v126, v120, v121
	s_nop 0
	v_addc_co_u32_e32 v15, vcc, 0, v151, vcc
	v_cvt_pk_bf16_f32 v127, v122, v123
	v_cvt_pk_bf16_f32 v104, v116, v117
	v_cvt_pk_bf16_f32 v105, v118, v119
	v_cvt_pk_bf16_f32 v106, v112, v113
	v_cvt_pk_bf16_f32 v107, v114, v115
	v_cvt_pk_bf16_f32 v88, v100, v101
	v_cvt_pk_bf16_f32 v89, v102, v103
	v_cvt_pk_bf16_f32 v90, v96, v97
	v_cvt_pk_bf16_f32 v91, v98, v99
	v_cvt_pk_bf16_f32 v72, v84, v85
	v_cvt_pk_bf16_f32 v73, v86, v87
	v_cvt_pk_bf16_f32 v74, v80, v81
	v_cvt_pk_bf16_f32 v75, v82, v83
	v_cvt_pk_bf16_f32 v71, v66, v67
	v_cvt_pk_bf16_f32 v63, v58, v59
	v_cvt_pk_bf16_f32 v40, v52, v53
	v_cvt_pk_bf16_f32 v41, v54, v55
	v_cvt_pk_bf16_f32 v42, v48, v49
	v_cvt_pk_bf16_f32 v43, v50, v51
	v_cvt_pk_bf16_f32 v24, v36, v37
	v_cvt_pk_bf16_f32 v25, v38, v39
	v_cvt_pk_bf16_f32 v26, v32, v33
	v_cvt_pk_bf16_f32 v27, v34, v35
	v_lshl_add_u64 v[12:13], v[150:151], 0, s[12:13]
	v_cvt_pk_bf16_f32 v8, v20, v21
	v_cvt_pk_bf16_f32 v9, v22, v23
	v_cvt_pk_bf16_f32 v10, v16, v17
	v_cvt_pk_bf16_f32 v11, v18, v19
	v_cvt_pk_bf16_f32 v4, v4, v5
	v_cvt_pk_bf16_f32 v5, v6, v7
	v_cvt_pk_bf16_f32 v6, v0, v1
	v_cvt_pk_bf16_f32 v7, v2, v3
	s_and_b64 vcc, exec, s[0:1]
	s_mov_b32 s41, s39
	s_mov_b32 s34, s40
	s_mov_b64 s[16:17], s[4:5]
	s_mov_b64 s[14:15], s[2:3]
	global_store_dwordx4 v[150:151], v[124:127], off
	global_store_dwordx4 v[110:111], v[104:107], off
	global_store_dwordx4 v[94:95], v[88:91], off
	global_store_dwordx4 v[78:79], v[72:75], off
	global_store_dwordx4 v[76:77], v[68:71], off offset:256
	global_store_dwordx4 v[56:57], v[60:63], off
	global_store_dwordx4 v[46:47], v[40:43], off
	global_store_dwordx4 v[30:31], v[24:27], off
	global_store_dwordx4 v[14:15], v[8:11], off
	global_store_dwordx4 v[12:13], v[4:7], off offset:256
	s_cbranch_vccz .LBB0_963
	s_waitcnt vmcnt(0)
	s_cmpk_gt_u32 s22, 0xff
	s_cbranch_scc1 .LBB0_978
	s_barrier

.LBB0_1200:
	s_waitcnt lgkmcnt(0)
	ds_read_b128 v[144:147], v151
	ds_read_b128 v[156:159], v151 offset:1024
	ds_read_b128 v[160:163], v151 offset:2048
	ds_read_b128 v[164:167], v151 offset:3072
	s_add_u32 s30, s28, 0xfff80080
	s_addc_u32 s31, s29, -1
	s_cmp_eq_u32 s56, 28
	s_cselect_b32 s35, s4, s31
	s_cselect_b32 s34, s7, s30
	s_cselect_b32 s31, s21, s55
	s_cselect_b32 s30, s23, s54
	v_lshl_add_u64 v[200:201], s[28:29], 0, v[136:137]
	s_add_i32 m0, s17, 0xc000
	ds_read_b128 v[168:171], v152
	ds_read_b128 v[172:175], v152 offset:1024
	ds_read_b128 v[176:179], v152 offset:2048
	ds_read_b128 v[180:183], v152 offset:3072
	ds_read_b128 v[184:187], v152 offset:4096
	ds_read_b128 v[188:191], v152 offset:5120
	ds_read_b128 v[192:195], v152 offset:6144
	ds_read_b128 v[196:199], v152 offset:7168
	global_load_lds_dwordx4 v[200:201], off
	v_lshl_add_u64 v[200:201], s[28:29], 0, v[138:139]
	s_add_i32 m0, s17, 0xe000
	s_nop 0
	global_load_lds_dwordx4 v[200:201], off
	s_waitcnt lgkmcnt(8)
	s_barrier
	s_waitcnt lgkmcnt(0)
	s_waitcnt lgkmcnt(0)
	v_mfma_f32_16x16x32_bf16 v[124:127], v[144:147], v[168:171], v[124:127]
	v_mfma_f32_16x16x32_bf16 v[120:123], v[160:163], v[168:171], v[120:123]
	v_mfma_f32_16x16x32_bf16 v[116:119], v[144:147], v[176:179], v[116:119]
	v_mfma_f32_16x16x32_bf16 v[112:115], v[160:163], v[176:179], v[112:115]
	v_mfma_f32_16x16x32_bf16 v[100:103], v[144:147], v[184:187], v[100:103]
	v_mfma_f32_16x16x32_bf16 v[96:99], v[160:163], v[184:187], v[96:99]
	v_mfma_f32_16x16x32_bf16 v[84:87], v[144:147], v[192:195], v[84:87]
	v_mfma_f32_16x16x32_bf16 v[80:83], v[160:163], v[192:195], v[80:83]
	v_mfma_f32_16x16x32_bf16 v[124:127], v[156:159], v[172:175], v[124:127]
	v_mfma_f32_16x16x32_bf16 v[120:123], v[164:167], v[172:175], v[120:123]
	v_mfma_f32_16x16x32_bf16 v[116:119], v[156:159], v[180:183], v[116:119]
	v_mfma_f32_16x16x32_bf16 v[112:115], v[164:167], v[180:183], v[112:115]
	v_mfma_f32_16x16x32_bf16 v[100:103], v[156:159], v[188:191], v[100:103]
	v_mfma_f32_16x16x32_bf16 v[96:99], v[164:167], v[188:191], v[96:99]
	v_mfma_f32_16x16x32_bf16 v[84:87], v[156:159], v[196:199], v[84:87]
	v_mfma_f32_16x16x32_bf16 v[80:83], v[164:167], v[196:199], v[80:83]
	s_barrier
	s_add_i32 s57, s45, s33
	v_lshl_add_u64 v[218:219], s[30:31], 0, v[130:131]
	s_mov_b32 m0, s57
	ds_read_b128 v[200:203], v153
	ds_read_b128 v[204:207], v153 offset:1024
	ds_read_b128 v[210:213], v153 offset:2048
	ds_read_b128 v[214:217], v153 offset:3072
	global_load_lds_dwordx4 v[218:219], off
	v_lshl_add_u64 v[220:221], s[30:31], 0, v[134:135]
	s_add_i32 m0, s57, 0x2000
	s_nop 0
	global_load_lds_dwordx4 v[220:221], off
	s_barrier
	s_waitcnt lgkmcnt(0)
	s_waitcnt lgkmcnt(0)
	v_mfma_f32_16x16x32_bf16 v[108:111], v[200:203], v[168:171], v[108:111]
	v_mfma_f32_16x16x32_bf16 v[104:107], v[210:213], v[168:171], v[104:107]
	v_mfma_f32_16x16x32_bf16 v[92:95], v[200:203], v[176:179], v[92:95]
	v_mfma_f32_16x16x32_bf16 v[88:91], v[210:213], v[176:179], v[88:91]
	v_mfma_f32_16x16x32_bf16 v[76:79], v[200:203], v[184:187], v[76:79]
	v_mfma_f32_16x16x32_bf16 v[72:75], v[210:213], v[184:187], v[72:75]
	v_mfma_f32_16x16x32_bf16 v[68:71], v[200:203], v[192:195], v[68:71]
	v_mfma_f32_16x16x32_bf16 v[64:67], v[210:213], v[192:195], v[64:67]
	v_mfma_f32_16x16x32_bf16 v[108:111], v[204:207], v[172:175], v[108:111]
	v_mfma_f32_16x16x32_bf16 v[104:107], v[214:217], v[172:175], v[104:107]
	v_mfma_f32_16x16x32_bf16 v[92:95], v[204:207], v[180:183], v[92:95]
	v_mfma_f32_16x16x32_bf16 v[88:91], v[214:217], v[180:183], v[88:91]
	v_mfma_f32_16x16x32_bf16 v[76:79], v[204:207], v[188:191], v[76:79]
	v_mfma_f32_16x16x32_bf16 v[72:75], v[214:217], v[188:191], v[72:75]
	v_mfma_f32_16x16x32_bf16 v[68:71], v[204:207], v[196:199], v[68:71]
	v_mfma_f32_16x16x32_bf16 v[64:67], v[214:217], v[196:199], v[64:67]
	s_mov_b32 m0, s17
	v_lshl_add_u64 v[222:223], s[34:35], 0, v[128:129]
	s_barrier
	ds_read_b128 v[168:171], v152 offset:16384
	ds_read_b128 v[172:175], v152 offset:17408
	ds_read_b128 v[176:179], v152 offset:18432
	ds_read_b128 v[180:183], v152 offset:19456
	ds_read_b128 v[184:187], v152 offset:20480
	ds_read_b128 v[188:191], v152 offset:21504
	ds_read_b128 v[192:195], v152 offset:22528
	ds_read_b128 v[196:199], v152 offset:23552
	global_load_lds_dwordx4 v[222:223], off
	v_lshl_add_u64 v[224:225], s[34:35], 0, v[132:133]
	s_mov_b32 m0, s38
	s_nop 0
	global_load_lds_dwordx4 v[224:225], off
	s_barrier
	s_waitcnt lgkmcnt(0)
	s_waitcnt lgkmcnt(0)
	v_mfma_f32_16x16x32_bf16 v[60:63], v[144:147], v[168:171], v[60:63]
	v_mfma_f32_16x16x32_bf16 v[56:59], v[160:163], v[168:171], v[56:59]
	v_mfma_f32_16x16x32_bf16 v[52:55], v[144:147], v[176:179], v[52:55]
	v_mfma_f32_16x16x32_bf16 v[48:51], v[160:163], v[176:179], v[48:51]
	v_mfma_f32_16x16x32_bf16 v[36:39], v[144:147], v[184:187], v[36:39]
	v_mfma_f32_16x16x32_bf16 v[32:35], v[160:163], v[184:187], v[32:35]
	v_mfma_f32_16x16x32_bf16 v[20:23], v[144:147], v[192:195], v[20:23]
	v_mfma_f32_16x16x32_bf16 v[16:19], v[160:163], v[192:195], v[16:19]
	v_mfma_f32_16x16x32_bf16 v[60:63], v[156:159], v[172:175], v[60:63]
	v_mfma_f32_16x16x32_bf16 v[56:59], v[164:167], v[172:175], v[56:59]
	v_mfma_f32_16x16x32_bf16 v[52:55], v[156:159], v[180:183], v[52:55]
	v_mfma_f32_16x16x32_bf16 v[48:51], v[164:167], v[180:183], v[48:51]
	v_mfma_f32_16x16x32_bf16 v[36:39], v[156:159], v[188:191], v[36:39]
	v_mfma_f32_16x16x32_bf16 v[32:35], v[164:167], v[188:191], v[32:35]
	v_mfma_f32_16x16x32_bf16 v[20:23], v[156:159], v[196:199], v[20:23]
	v_mfma_f32_16x16x32_bf16 v[16:19], v[164:167], v[196:199], v[16:19]
	s_barrier
	s_add_u32 s60, s30, 0x80000
	s_addc_u32 s61, s31, 0
	s_add_i32 s57, s51, s33
	v_lshl_add_u64 v[144:145], s[60:61], 0, v[130:131]
	s_mov_b32 m0, s57
	s_nop 0
	global_load_lds_dwordx4 v[144:145], off
	v_lshl_add_u64 v[144:145], s[60:61], 0, v[134:135]
	s_add_i32 m0, s57, 0x2000
	s_nop 0
	global_load_lds_dwordx4 v[144:145], off
	s_waitcnt vmcnt(6)
	s_barrier
	v_mfma_f32_16x16x32_bf16 v[44:47], v[200:203], v[168:171], v[44:47]
	v_mfma_f32_16x16x32_bf16 v[40:43], v[210:213], v[168:171], v[40:43]
	v_mfma_f32_16x16x32_bf16 v[28:31], v[200:203], v[176:179], v[28:31]
	v_mfma_f32_16x16x32_bf16 v[24:27], v[210:213], v[176:179], v[24:27]
	v_mfma_f32_16x16x32_bf16 v[12:15], v[200:203], v[184:187], v[12:15]
	v_mfma_f32_16x16x32_bf16 v[8:11], v[210:213], v[184:187], v[8:11]
	v_mfma_f32_16x16x32_bf16 v[4:7], v[200:203], v[192:195], v[4:7]
	v_mfma_f32_16x16x32_bf16 v[0:3], v[210:213], v[192:195], v[0:3]
	v_mfma_f32_16x16x32_bf16 v[44:47], v[204:207], v[172:175], v[44:47]
	v_mfma_f32_16x16x32_bf16 v[40:43], v[214:217], v[172:175], v[40:43]
	v_mfma_f32_16x16x32_bf16 v[28:31], v[204:207], v[180:183], v[28:31]
	v_mfma_f32_16x16x32_bf16 v[24:27], v[214:217], v[180:183], v[24:27]
	v_mfma_f32_16x16x32_bf16 v[12:15], v[204:207], v[188:191], v[12:15]
	v_mfma_f32_16x16x32_bf16 v[8:11], v[214:217], v[188:191], v[8:11]
	v_mfma_f32_16x16x32_bf16 v[4:7], v[204:207], v[196:199], v[4:7]
	v_mfma_f32_16x16x32_bf16 v[0:3], v[214:217], v[196:199], v[0:3]
	s_add_i32 s57, 0, 0x18000
	v_add_u32_e32 v155, s57, v150
	s_barrier
	ds_read_b128 v[144:147], v155
	ds_read_b128 v[156:159], v155 offset:1024
	ds_read_b128 v[160:163], v155 offset:2048
	ds_read_b128 v[164:167], v155 offset:3072
	s_add_u32 s34, s34, 0x80000
	s_addc_u32 s35, s35, 0
	s_mov_b32 m0, s39
	v_lshl_add_u64 v[200:201], s[34:35], 0, v[128:129]
	ds_read_b128 v[168:171], v152 offset:32768
	ds_read_b128 v[172:175], v152 offset:33792
	ds_read_b128 v[176:179], v152 offset:34816
	ds_read_b128 v[180:183], v152 offset:35840
	ds_read_b128 v[184:187], v152 offset:36864
	ds_read_b128 v[188:191], v152 offset:37888
	ds_read_b128 v[192:195], v152 offset:38912
	ds_read_b128 v[196:199], v152 offset:39936
	global_load_lds_dwordx4 v[200:201], off
	v_lshl_add_u64 v[200:201], s[34:35], 0, v[132:133]
	s_mov_b32 m0, s40
	s_nop 0
	global_load_lds_dwordx4 v[200:201], off
	s_waitcnt lgkmcnt(8)
	s_barrier
	s_waitcnt lgkmcnt(0)
	s_waitcnt lgkmcnt(0)
	v_mfma_f32_16x16x32_bf16 v[124:127], v[144:147], v[168:171], v[124:127]
	v_mfma_f32_16x16x32_bf16 v[120:123], v[160:163], v[168:171], v[120:123]
	v_mfma_f32_16x16x32_bf16 v[116:119], v[144:147], v[176:179], v[116:119]
	v_mfma_f32_16x16x32_bf16 v[112:115], v[160:163], v[176:179], v[112:115]
	v_mfma_f32_16x16x32_bf16 v[100:103], v[144:147], v[184:187], v[100:103]
	v_mfma_f32_16x16x32_bf16 v[96:99], v[160:163], v[184:187], v[96:99]
	v_mfma_f32_16x16x32_bf16 v[84:87], v[144:147], v[192:195], v[84:87]
	v_mfma_f32_16x16x32_bf16 v[80:83], v[160:163], v[192:195], v[80:83]
	v_mfma_f32_16x16x32_bf16 v[124:127], v[156:159], v[172:175], v[124:127]
	v_mfma_f32_16x16x32_bf16 v[120:123], v[164:167], v[172:175], v[120:123]
	v_mfma_f32_16x16x32_bf16 v[116:119], v[156:159], v[180:183], v[116:119]
	v_mfma_f32_16x16x32_bf16 v[112:115], v[164:167], v[180:183], v[112:115]
	v_mfma_f32_16x16x32_bf16 v[100:103], v[156:159], v[188:191], v[100:103]
	v_mfma_f32_16x16x32_bf16 v[96:99], v[164:167], v[188:191], v[96:99]
	v_mfma_f32_16x16x32_bf16 v[84:87], v[156:159], v[196:199], v[84:87]
	v_mfma_f32_16x16x32_bf16 v[80:83], v[164:167], v[196:199], v[80:83]
	s_barrier
	s_add_i32 s34, 0, 0x1c000
	s_add_i32 s35, s57, s33
	v_add_u32_e32 v155, s34, v150
	v_lshl_add_u64 v[218:219], v[218:219], 0, s[8:9]
	s_mov_b32 m0, s35
	ds_read_b128 v[200:203], v155
	ds_read_b128 v[204:207], v155 offset:1024
	ds_read_b128 v[210:213], v155 offset:2048
	ds_read_b128 v[214:217], v155 offset:3072
	global_load_lds_dwordx4 v[218:219], off
	v_lshl_add_u64 v[218:219], v[220:221], 0, s[8:9]
	s_add_i32 m0, s35, 0x2000
	s_nop 0
	global_load_lds_dwordx4 v[218:219], off
	s_barrier
	s_waitcnt lgkmcnt(0)
	s_waitcnt lgkmcnt(0)
	v_mfma_f32_16x16x32_bf16 v[108:111], v[200:203], v[168:171], v[108:111]
	v_mfma_f32_16x16x32_bf16 v[104:107], v[210:213], v[168:171], v[104:107]
	v_mfma_f32_16x16x32_bf16 v[92:95], v[200:203], v[176:179], v[92:95]
	v_mfma_f32_16x16x32_bf16 v[88:91], v[210:213], v[176:179], v[88:91]
	v_mfma_f32_16x16x32_bf16 v[76:79], v[200:203], v[184:187], v[76:79]
	v_mfma_f32_16x16x32_bf16 v[72:75], v[210:213], v[184:187], v[72:75]
	v_mfma_f32_16x16x32_bf16 v[68:71], v[200:203], v[192:195], v[68:71]
	v_mfma_f32_16x16x32_bf16 v[64:67], v[210:213], v[192:195], v[64:67]
	v_mfma_f32_16x16x32_bf16 v[108:111], v[204:207], v[172:175], v[108:111]
	v_mfma_f32_16x16x32_bf16 v[104:107], v[214:217], v[172:175], v[104:107]
	v_mfma_f32_16x16x32_bf16 v[92:95], v[204:207], v[180:183], v[92:95]
	v_mfma_f32_16x16x32_bf16 v[88:91], v[214:217], v[180:183], v[88:91]
	v_mfma_f32_16x16x32_bf16 v[76:79], v[204:207], v[188:191], v[76:79]
	v_mfma_f32_16x16x32_bf16 v[72:75], v[214:217], v[188:191], v[72:75]
	v_mfma_f32_16x16x32_bf16 v[68:71], v[204:207], v[196:199], v[68:71]
	v_mfma_f32_16x16x32_bf16 v[64:67], v[214:217], v[196:199], v[64:67]
	s_mov_b32 m0, s43
	v_lshl_add_u64 v[218:219], v[222:223], 0, s[8:9]
	s_barrier
	ds_read_b128 v[168:171], v152 offset:49152
	ds_read_b128 v[172:175], v152 offset:50176
	ds_read_b128 v[176:179], v152 offset:51200
	ds_read_b128 v[180:183], v152 offset:52224
	ds_read_b128 v[184:187], v152 offset:53248
	ds_read_b128 v[188:191], v152 offset:54272
	ds_read_b128 v[192:195], v152 offset:55296
	ds_read_b128 v[196:199], v152 offset:56320
	global_load_lds_dwordx4 v[218:219], off
	v_lshl_add_u64 v[218:219], v[224:225], 0, s[8:9]
	s_mov_b32 m0, s44
	s_nop 0
	global_load_lds_dwordx4 v[218:219], off
	s_barrier
	s_waitcnt lgkmcnt(0)
	s_waitcnt lgkmcnt(0)
	v_mfma_f32_16x16x32_bf16 v[60:63], v[144:147], v[168:171], v[60:63]
	v_mfma_f32_16x16x32_bf16 v[56:59], v[160:163], v[168:171], v[56:59]
	v_mfma_f32_16x16x32_bf16 v[52:55], v[144:147], v[176:179], v[52:55]
	v_mfma_f32_16x16x32_bf16 v[48:51], v[160:163], v[176:179], v[48:51]
	v_mfma_f32_16x16x32_bf16 v[36:39], v[144:147], v[184:187], v[36:39]
	v_mfma_f32_16x16x32_bf16 v[32:35], v[160:163], v[184:187], v[32:35]
	v_mfma_f32_16x16x32_bf16 v[20:23], v[144:147], v[192:195], v[20:23]
	v_mfma_f32_16x16x32_bf16 v[16:19], v[160:163], v[192:195], v[16:19]
	v_mfma_f32_16x16x32_bf16 v[60:63], v[156:159], v[172:175], v[60:63]
	v_mfma_f32_16x16x32_bf16 v[56:59], v[164:167], v[172:175], v[56:59]
	v_mfma_f32_16x16x32_bf16 v[52:55], v[156:159], v[180:183], v[52:55]
	v_mfma_f32_16x16x32_bf16 v[48:51], v[164:167], v[180:183], v[48:51]
	v_mfma_f32_16x16x32_bf16 v[36:39], v[156:159], v[188:191], v[36:39]
	v_mfma_f32_16x16x32_bf16 v[32:35], v[164:167], v[188:191], v[32:35]
	v_mfma_f32_16x16x32_bf16 v[20:23], v[156:159], v[196:199], v[20:23]
	v_mfma_f32_16x16x32_bf16 v[16:19], v[164:167], v[196:199], v[16:19]
	s_barrier
	s_add_u32 s30, s30, 0x80080
	s_addc_u32 s31, s31, 0
	s_add_i32 s34, s34, s33
	v_lshl_add_u64 v[144:145], s[30:31], 0, v[130:131]
	s_mov_b32 m0, s34
	s_nop 0
	global_load_lds_dwordx4 v[144:145], off
	v_lshl_add_u64 v[144:145], s[30:31], 0, v[134:135]
	s_add_i32 m0, s34, 0x2000
	s_nop 0
	global_load_lds_dwordx4 v[144:145], off
	s_waitcnt vmcnt(6)
	s_barrier
	v_mfma_f32_16x16x32_bf16 v[44:47], v[200:203], v[168:171], v[44:47]
	v_mfma_f32_16x16x32_bf16 v[40:43], v[210:213], v[168:171], v[40:43]
	v_mfma_f32_16x16x32_bf16 v[28:31], v[200:203], v[176:179], v[28:31]
	v_mfma_f32_16x16x32_bf16 v[24:27], v[210:213], v[176:179], v[24:27]
	v_mfma_f32_16x16x32_bf16 v[12:15], v[200:203], v[184:187], v[12:15]
	v_mfma_f32_16x16x32_bf16 v[8:11], v[210:213], v[184:187], v[8:11]
	v_mfma_f32_16x16x32_bf16 v[4:7], v[200:203], v[192:195], v[4:7]
	v_mfma_f32_16x16x32_bf16 v[0:3], v[210:213], v[192:195], v[0:3]
	v_mfma_f32_16x16x32_bf16 v[44:47], v[204:207], v[172:175], v[44:47]
	v_mfma_f32_16x16x32_bf16 v[40:43], v[214:217], v[172:175], v[40:43]
	v_mfma_f32_16x16x32_bf16 v[28:31], v[204:207], v[180:183], v[28:31]
	v_mfma_f32_16x16x32_bf16 v[24:27], v[214:217], v[180:183], v[24:27]
	v_mfma_f32_16x16x32_bf16 v[12:15], v[204:207], v[188:191], v[12:15]
	v_mfma_f32_16x16x32_bf16 v[8:11], v[214:217], v[188:191], v[8:11]
	v_mfma_f32_16x16x32_bf16 v[4:7], v[204:207], v[196:199], v[4:7]
	v_mfma_f32_16x16x32_bf16 v[0:3], v[214:217], v[196:199], v[0:3]
	s_add_i32 s56, s56, 2
	s_add_u32 s28, s28, 0x100
	s_addc_u32 s29, s29, 0
	s_add_u32 s54, s54, 0x100
	s_addc_u32 s55, s55, 0
	s_cmp_gt_u32 s56, 29
	s_barrier
	s_cbranch_scc0 .LBB0_1200
	v_mov_b32_e32 v155, v148
	v_mov_b32_e32 v156, v149
	s_cmp_gt_i32 s6, 7
	s_mov_b64 s[28:29], -1
	s_cbranch_scc0 .LBB0_1231
	s_cmp_gt_u32 s6, 15
	s_cbranch_scc0 .LBB0_1212
	s_cmp_gt_u32 s6, 23
	s_cbranch_scc0 .LBB0_1209
	s_lshl_b32 s4, s16, 8
	s_add_i32 s4, s4, s41
	v_lshl_add_u32 v144, v156, 3, s42
	v_add_u32_e32 v157, s4, v155
	v_ashrrev_i32_e32 v145, 31, v144
	v_mad_i64_i32 v[146:147], s[28:29], v157, s52, 0
	s_cmp_gt_u32 s6, 25
	s_mov_b64 s[28:29], -1
	v_lshl_add_u64 v[146:147], s[14:15], 0, v[146:147]
	v_lshlrev_b64 v[144:145], 1, v[144:145]
	v_add_u32_e32 v163, 16, v157
	v_add_u32_e32 v162, 32, v157
	v_add_u32_e32 v161, 48, v157
	v_add_u32_e32 v160, 0x80, v157
	v_add_u32_e32 v159, 0x90, v157
	v_add_u32_e32 v158, 0xa0, v157
	v_add_u32_e32 v157, 0xb0, v157
	s_cbranch_scc0 .LBB0_1206
	s_lshl_b32 s4, s6, 9
	v_lshl_add_u64 v[168:169], v[146:147], 0, s[4:5]
	v_cvt_pk_bf16_f32 v164, v124, v125
	v_cvt_pk_bf16_f32 v165, v126, v127
	v_cvt_pk_bf16_f32 v166, v120, v121
	v_cvt_pk_bf16_f32 v167, v122, v123
	v_lshl_add_u64 v[168:169], v[168:169], 0, v[144:145]
	global_store_dwordx4 v[168:169], v[164:167], off
	s_nop 1
	v_cvt_pk_bf16_f32 v164, v108, v109
	v_cvt_pk_bf16_f32 v165, v110, v111
	v_cvt_pk_bf16_f32 v166, v104, v105
	v_cvt_pk_bf16_f32 v167, v106, v107
	global_store_dwordx4 v[168:169], v[164:167], off offset:256
	v_mov_b64_e32 v[168:169], s[14:15]
	v_mad_i64_i32 v[170:171], s[28:29], v163, s52, v[168:169]
	v_lshl_add_u64 v[170:171], v[170:171], 0, s[4:5]
	v_cvt_pk_bf16_f32 v164, v116, v117
	v_cvt_pk_bf16_f32 v165, v118, v119
	v_cvt_pk_bf16_f32 v166, v112, v113
	v_cvt_pk_bf16_f32 v167, v114, v115
	v_lshl_add_u64 v[170:171], v[170:171], 0, v[144:145]
	global_store_dwordx4 v[170:171], v[164:167], off
	s_nop 1
	v_cvt_pk_bf16_f32 v164, v92, v93
	v_cvt_pk_bf16_f32 v165, v94, v95
	v_cvt_pk_bf16_f32 v166, v88, v89
	v_cvt_pk_bf16_f32 v167, v90, v91
	global_store_dwordx4 v[170:171], v[164:167], off offset:256
	v_mad_i64_i32 v[170:171], s[28:29], v162, s52, v[168:169]
	v_lshl_add_u64 v[170:171], v[170:171], 0, s[4:5]
	v_cvt_pk_bf16_f32 v164, v100, v101
	v_cvt_pk_bf16_f32 v165, v102, v103
	v_cvt_pk_bf16_f32 v166, v96, v97
	v_cvt_pk_bf16_f32 v167, v98, v99
	v_lshl_add_u64 v[170:171], v[170:171], 0, v[144:145]
	global_store_dwordx4 v[170:171], v[164:167], off
	s_nop 1
	v_cvt_pk_bf16_f32 v164, v76, v77
	v_cvt_pk_bf16_f32 v165, v78, v79
	v_cvt_pk_bf16_f32 v166, v72, v73
	v_cvt_pk_bf16_f32 v167, v74, v75
	global_store_dwordx4 v[170:171], v[164:167], off offset:256
	v_mad_i64_i32 v[170:171], s[28:29], v161, s52, v[168:169]
	v_lshl_add_u64 v[170:171], v[170:171], 0, s[4:5]
	v_cvt_pk_bf16_f32 v164, v84, v85
	v_cvt_pk_bf16_f32 v165, v86, v87
	v_cvt_pk_bf16_f32 v166, v80, v81
	v_cvt_pk_bf16_f32 v167, v82, v83
	v_lshl_add_u64 v[170:171], v[170:171], 0, v[144:145]
	global_store_dwordx4 v[170:171], v[164:167], off
	s_nop 1
	v_cvt_pk_bf16_f32 v164, v68, v69
	v_cvt_pk_bf16_f32 v165, v70, v71
	v_cvt_pk_bf16_f32 v166, v64, v65
	v_cvt_pk_bf16_f32 v167, v66, v67
	global_store_dwordx4 v[170:171], v[164:167], off offset:256
	v_mad_i64_i32 v[170:171], s[28:29], v160, s52, v[168:169]
	v_lshl_add_u64 v[170:171], v[170:171], 0, s[4:5]
	v_cvt_pk_bf16_f32 v164, v60, v61
	v_cvt_pk_bf16_f32 v165, v62, v63
	v_cvt_pk_bf16_f32 v166, v56, v57
	v_cvt_pk_bf16_f32 v167, v58, v59
	v_lshl_add_u64 v[170:171], v[170:171], 0, v[144:145]
	global_store_dwordx4 v[170:171], v[164:167], off
	s_nop 1
	v_cvt_pk_bf16_f32 v164, v44, v45
	v_cvt_pk_bf16_f32 v165, v46, v47
	v_cvt_pk_bf16_f32 v166, v40, v41
	v_cvt_pk_bf16_f32 v167, v42, v43
	global_store_dwordx4 v[170:171], v[164:167], off offset:256
	v_mad_i64_i32 v[170:171], s[28:29], v159, s52, v[168:169]
	v_lshl_add_u64 v[170:171], v[170:171], 0, s[4:5]
	v_cvt_pk_bf16_f32 v164, v52, v53
	v_cvt_pk_bf16_f32 v165, v54, v55
	v_cvt_pk_bf16_f32 v166, v48, v49
	v_cvt_pk_bf16_f32 v167, v50, v51
	v_lshl_add_u64 v[170:171], v[170:171], 0, v[144:145]
	global_store_dwordx4 v[170:171], v[164:167], off
	s_nop 1
	v_cvt_pk_bf16_f32 v164, v28, v29
	v_cvt_pk_bf16_f32 v165, v30, v31
	v_cvt_pk_bf16_f32 v166, v24, v25
	v_cvt_pk_bf16_f32 v167, v26, v27
	global_store_dwordx4 v[170:171], v[164:167], off offset:256
	v_mad_i64_i32 v[170:171], s[28:29], v158, s52, v[168:169]
	v_lshl_add_u64 v[170:171], v[170:171], 0, s[4:5]
	v_cvt_pk_bf16_f32 v164, v36, v37
	v_cvt_pk_bf16_f32 v165, v38, v39
	v_cvt_pk_bf16_f32 v166, v32, v33
	v_cvt_pk_bf16_f32 v167, v34, v35
	v_lshl_add_u64 v[170:171], v[170:171], 0, v[144:145]
	v_mad_i64_i32 v[168:169], s[28:29], v157, s52, v[168:169]
	global_store_dwordx4 v[170:171], v[164:167], off
	v_lshl_add_u64 v[168:169], v[168:169], 0, s[4:5]
	v_lshl_add_u64 v[168:169], v[168:169], 0, v[144:145]
	v_cvt_pk_bf16_f32 v164, v12, v13
	v_cvt_pk_bf16_f32 v165, v14, v15
	v_cvt_pk_bf16_f32 v166, v8, v9
	v_cvt_pk_bf16_f32 v167, v10, v11
	global_store_dwordx4 v[170:171], v[164:167], off offset:256
	s_mov_b64 s[28:29], 0
	s_nop 0
	v_cvt_pk_bf16_f32 v164, v20, v21
	v_cvt_pk_bf16_f32 v165, v22, v23
	v_cvt_pk_bf16_f32 v166, v16, v17
	v_cvt_pk_bf16_f32 v167, v18, v19
	global_store_dwordx4 v[168:169], v[164:167], off
	s_nop 1
	v_cvt_pk_bf16_f32 v164, v4, v5
	v_cvt_pk_bf16_f32 v165, v6, v7
	v_cvt_pk_bf16_f32 v166, v0, v1
	v_cvt_pk_bf16_f32 v167, v2, v3
	global_store_dwordx4 v[168:169], v[164:167], off offset:256

.LBB0_1402:
	ds_read_b128 v[150:153], v147
	ds_read_b128 v[154:157], v147 offset:1024
	ds_read_b128 v[158:161], v147 offset:2048
	ds_read_b128 v[162:165], v147 offset:3072
	s_add_u32 s34, s30, 0x100
	s_addc_u32 s35, s31, 0
	s_cmp_eq_u32 s69, 36
	s_cselect_b32 s39, s5, s35
	s_cselect_b32 s38, s4, s34
	s_cselect_b32 s37, s7, s68
	s_cselect_b32 s36, s6, s67
	v_lshl_add_u64 v[198:199], s[30:31], 0, v[136:137]
	s_add_i32 m0, s41, 0xc000
	ds_read_b128 v[166:169], v148
	ds_read_b128 v[170:173], v148 offset:1024
	ds_read_b128 v[174:177], v148 offset:2048
	ds_read_b128 v[178:181], v148 offset:3072
	ds_read_b128 v[182:185], v148 offset:4096
	ds_read_b128 v[186:189], v148 offset:5120
	ds_read_b128 v[190:193], v148 offset:6144
	ds_read_b128 v[194:197], v148 offset:7168
	global_load_lds_dwordx4 v[198:199], off
	v_lshl_add_u64 v[198:199], s[30:31], 0, v[138:139]
	s_add_i32 m0, s41, 0xe000
	s_nop 0
	global_load_lds_dwordx4 v[198:199], off
	s_waitcnt lgkmcnt(8)
	s_barrier
	s_waitcnt lgkmcnt(0)
	s_waitcnt lgkmcnt(0)
	v_mfma_f32_16x16x32_bf16 v[124:127], v[150:153], v[166:169], v[124:127]
	v_mfma_f32_16x16x32_bf16 v[120:123], v[158:161], v[166:169], v[120:123]
	v_mfma_f32_16x16x32_bf16 v[116:119], v[150:153], v[174:177], v[116:119]
	v_mfma_f32_16x16x32_bf16 v[112:115], v[158:161], v[174:177], v[112:115]
	v_mfma_f32_16x16x32_bf16 v[100:103], v[150:153], v[182:185], v[100:103]
	v_mfma_f32_16x16x32_bf16 v[96:99], v[158:161], v[182:185], v[96:99]
	v_mfma_f32_16x16x32_bf16 v[84:87], v[150:153], v[190:193], v[84:87]
	v_mfma_f32_16x16x32_bf16 v[80:83], v[158:161], v[190:193], v[80:83]
	v_mfma_f32_16x16x32_bf16 v[124:127], v[154:157], v[170:173], v[124:127]
	v_mfma_f32_16x16x32_bf16 v[120:123], v[162:165], v[170:173], v[120:123]
	v_mfma_f32_16x16x32_bf16 v[116:119], v[154:157], v[178:181], v[116:119]
	v_mfma_f32_16x16x32_bf16 v[112:115], v[162:165], v[178:181], v[112:115]
	v_mfma_f32_16x16x32_bf16 v[100:103], v[154:157], v[186:189], v[100:103]
	v_mfma_f32_16x16x32_bf16 v[96:99], v[162:165], v[186:189], v[96:99]
	v_mfma_f32_16x16x32_bf16 v[84:87], v[154:157], v[194:197], v[84:87]
	v_mfma_f32_16x16x32_bf16 v[80:83], v[162:165], v[194:197], v[80:83]
	s_barrier
	s_add_i32 s30, s54, s40
	v_lshl_add_u64 v[206:207], s[36:37], 0, v[130:131]
	s_mov_b32 m0, s30
	ds_read_b128 v[198:201], v149
	ds_read_b128 v[202:205], v149 offset:1024
	ds_read_b128 v[210:213], v149 offset:2048
	ds_read_b128 v[214:217], v149 offset:3072
	global_load_lds_dwordx4 v[206:207], off
	v_lshl_add_u64 v[218:219], s[36:37], 0, v[134:135]
	s_add_i32 m0, s30, 0x2000
	s_nop 0
	global_load_lds_dwordx4 v[218:219], off
	s_barrier
	s_waitcnt lgkmcnt(0)
	s_waitcnt lgkmcnt(0)
	v_mfma_f32_16x16x32_bf16 v[108:111], v[198:201], v[166:169], v[108:111]
	v_mfma_f32_16x16x32_bf16 v[104:107], v[210:213], v[166:169], v[104:107]
	v_mfma_f32_16x16x32_bf16 v[92:95], v[198:201], v[174:177], v[92:95]
	v_mfma_f32_16x16x32_bf16 v[88:91], v[210:213], v[174:177], v[88:91]
	v_mfma_f32_16x16x32_bf16 v[76:79], v[198:201], v[182:185], v[76:79]
	v_mfma_f32_16x16x32_bf16 v[72:75], v[210:213], v[182:185], v[72:75]
	v_mfma_f32_16x16x32_bf16 v[68:71], v[198:201], v[190:193], v[68:71]
	v_mfma_f32_16x16x32_bf16 v[64:67], v[210:213], v[190:193], v[64:67]
	v_mfma_f32_16x16x32_bf16 v[108:111], v[202:205], v[170:173], v[108:111]
	v_mfma_f32_16x16x32_bf16 v[104:107], v[214:217], v[170:173], v[104:107]
	v_mfma_f32_16x16x32_bf16 v[92:95], v[202:205], v[178:181], v[92:95]
	v_mfma_f32_16x16x32_bf16 v[88:91], v[214:217], v[178:181], v[88:91]
	v_mfma_f32_16x16x32_bf16 v[76:79], v[202:205], v[186:189], v[76:79]
	v_mfma_f32_16x16x32_bf16 v[72:75], v[214:217], v[186:189], v[72:75]
	v_mfma_f32_16x16x32_bf16 v[68:71], v[202:205], v[194:197], v[68:71]
	v_mfma_f32_16x16x32_bf16 v[64:67], v[214:217], v[194:197], v[64:67]
	s_mov_b32 m0, s41
	v_lshl_add_u64 v[220:221], s[38:39], 0, v[128:129]
	s_barrier
	ds_read_b128 v[166:169], v148 offset:16384
	ds_read_b128 v[170:173], v148 offset:17408
	ds_read_b128 v[174:177], v148 offset:18432
	ds_read_b128 v[178:181], v148 offset:19456
	ds_read_b128 v[182:185], v148 offset:20480
	ds_read_b128 v[186:189], v148 offset:21504
	ds_read_b128 v[190:193], v148 offset:22528
	ds_read_b128 v[194:197], v148 offset:23552
	global_load_lds_dwordx4 v[220:221], off
	v_lshl_add_u64 v[222:223], s[38:39], 0, v[132:133]
	s_mov_b32 m0, s42
	s_nop 0
	global_load_lds_dwordx4 v[222:223], off
	s_barrier
	s_waitcnt lgkmcnt(0)
	s_waitcnt lgkmcnt(0)
	v_mfma_f32_16x16x32_bf16 v[60:63], v[150:153], v[166:169], v[60:63]
	v_mfma_f32_16x16x32_bf16 v[56:59], v[158:161], v[166:169], v[56:59]
	v_mfma_f32_16x16x32_bf16 v[52:55], v[150:153], v[174:177], v[52:55]
	v_mfma_f32_16x16x32_bf16 v[48:51], v[158:161], v[174:177], v[48:51]
	v_mfma_f32_16x16x32_bf16 v[36:39], v[150:153], v[182:185], v[36:39]
	v_mfma_f32_16x16x32_bf16 v[32:35], v[158:161], v[182:185], v[32:35]
	v_mfma_f32_16x16x32_bf16 v[20:23], v[150:153], v[190:193], v[20:23]
	v_mfma_f32_16x16x32_bf16 v[16:19], v[158:161], v[190:193], v[16:19]
	v_mfma_f32_16x16x32_bf16 v[60:63], v[154:157], v[170:173], v[60:63]
	v_mfma_f32_16x16x32_bf16 v[56:59], v[162:165], v[170:173], v[56:59]
	v_mfma_f32_16x16x32_bf16 v[52:55], v[154:157], v[178:181], v[52:55]
	v_mfma_f32_16x16x32_bf16 v[48:51], v[162:165], v[178:181], v[48:51]
	v_mfma_f32_16x16x32_bf16 v[36:39], v[154:157], v[186:189], v[36:39]
	v_mfma_f32_16x16x32_bf16 v[32:35], v[162:165], v[186:189], v[32:35]
	v_mfma_f32_16x16x32_bf16 v[20:23], v[154:157], v[194:197], v[20:23]
	v_mfma_f32_16x16x32_bf16 v[16:19], v[162:165], v[194:197], v[16:19]
	s_barrier
	s_add_u32 s30, s36, 0xa0000
	s_addc_u32 s31, s37, 0
	s_add_i32 s70, s55, s40
	v_lshl_add_u64 v[150:151], s[30:31], 0, v[130:131]
	s_mov_b32 m0, s70
	s_nop 0
	global_load_lds_dwordx4 v[150:151], off
	v_lshl_add_u64 v[150:151], s[30:31], 0, v[134:135]
	s_add_i32 m0, s70, 0x2000
	s_nop 0
	global_load_lds_dwordx4 v[150:151], off
	s_waitcnt vmcnt(6)
	s_barrier
	v_mfma_f32_16x16x32_bf16 v[44:47], v[198:201], v[166:169], v[44:47]
	v_mfma_f32_16x16x32_bf16 v[40:43], v[210:213], v[166:169], v[40:43]
	v_mfma_f32_16x16x32_bf16 v[28:31], v[198:201], v[174:177], v[28:31]
	v_mfma_f32_16x16x32_bf16 v[24:27], v[210:213], v[174:177], v[24:27]
	v_mfma_f32_16x16x32_bf16 v[12:15], v[198:201], v[182:185], v[12:15]
	v_mfma_f32_16x16x32_bf16 v[8:11], v[210:213], v[182:185], v[8:11]
	v_mfma_f32_16x16x32_bf16 v[4:7], v[198:201], v[190:193], v[4:7]
	v_mfma_f32_16x16x32_bf16 v[0:3], v[210:213], v[190:193], v[0:3]
	v_mfma_f32_16x16x32_bf16 v[44:47], v[202:205], v[170:173], v[44:47]
	v_mfma_f32_16x16x32_bf16 v[40:43], v[214:217], v[170:173], v[40:43]
	v_mfma_f32_16x16x32_bf16 v[28:31], v[202:205], v[178:181], v[28:31]
	v_mfma_f32_16x16x32_bf16 v[24:27], v[214:217], v[178:181], v[24:27]
	v_mfma_f32_16x16x32_bf16 v[12:15], v[202:205], v[186:189], v[12:15]
	v_mfma_f32_16x16x32_bf16 v[8:11], v[214:217], v[186:189], v[8:11]
	v_mfma_f32_16x16x32_bf16 v[4:7], v[202:205], v[194:197], v[4:7]
	v_mfma_f32_16x16x32_bf16 v[0:3], v[214:217], v[194:197], v[0:3]
	s_add_i32 s70, 0, 0x18000
	v_add_u32_e32 v162, s70, v146
	s_barrier
	ds_read_b128 v[150:153], v162
	ds_read_b128 v[154:157], v162 offset:1024
	ds_read_b128 v[158:161], v162 offset:2048
	ds_read_b128 v[162:165], v162 offset:3072
	s_add_u32 s30, s38, 0xa0000
	s_addc_u32 s31, s39, 0
	s_mov_b32 m0, s43
	v_lshl_add_u64 v[198:199], s[30:31], 0, v[128:129]
	ds_read_b128 v[166:169], v148 offset:32768
	ds_read_b128 v[170:173], v148 offset:33792
	ds_read_b128 v[174:177], v148 offset:34816
	ds_read_b128 v[178:181], v148 offset:35840
	ds_read_b128 v[182:185], v148 offset:36864
	ds_read_b128 v[186:189], v148 offset:37888
	ds_read_b128 v[190:193], v148 offset:38912
	ds_read_b128 v[194:197], v148 offset:39936
	global_load_lds_dwordx4 v[198:199], off
	v_lshl_add_u64 v[198:199], s[30:31], 0, v[132:133]
	s_mov_b32 m0, s44
	s_nop 0
	global_load_lds_dwordx4 v[198:199], off
	s_waitcnt lgkmcnt(8)
	s_barrier
	s_waitcnt lgkmcnt(0)
	s_waitcnt lgkmcnt(0)
	v_mfma_f32_16x16x32_bf16 v[124:127], v[150:153], v[166:169], v[124:127]
	v_mfma_f32_16x16x32_bf16 v[120:123], v[158:161], v[166:169], v[120:123]
	v_mfma_f32_16x16x32_bf16 v[116:119], v[150:153], v[174:177], v[116:119]
	v_mfma_f32_16x16x32_bf16 v[112:115], v[158:161], v[174:177], v[112:115]
	v_mfma_f32_16x16x32_bf16 v[100:103], v[150:153], v[182:185], v[100:103]
	v_mfma_f32_16x16x32_bf16 v[96:99], v[158:161], v[182:185], v[96:99]
	v_mfma_f32_16x16x32_bf16 v[84:87], v[150:153], v[190:193], v[84:87]
	v_mfma_f32_16x16x32_bf16 v[80:83], v[158:161], v[190:193], v[80:83]
	v_mfma_f32_16x16x32_bf16 v[124:127], v[154:157], v[170:173], v[124:127]
	v_mfma_f32_16x16x32_bf16 v[120:123], v[162:165], v[170:173], v[120:123]
	v_mfma_f32_16x16x32_bf16 v[116:119], v[154:157], v[178:181], v[116:119]
	v_mfma_f32_16x16x32_bf16 v[112:115], v[162:165], v[178:181], v[112:115]
	v_mfma_f32_16x16x32_bf16 v[100:103], v[154:157], v[186:189], v[100:103]
	v_mfma_f32_16x16x32_bf16 v[96:99], v[162:165], v[186:189], v[96:99]
	v_mfma_f32_16x16x32_bf16 v[84:87], v[154:157], v[194:197], v[84:87]
	v_mfma_f32_16x16x32_bf16 v[80:83], v[162:165], v[194:197], v[80:83]
	s_barrier
	s_add_i32 s38, 0, 0x1c000
	s_add_i32 s30, s70, s40
	v_add_u32_e32 v214, s38, v146
	v_lshl_add_u64 v[206:207], v[206:207], 0, s[14:15]
	s_mov_b32 m0, s30
	ds_read_b128 v[198:201], v214
	ds_read_b128 v[202:205], v214 offset:1024
	ds_read_b128 v[210:213], v214 offset:2048
	ds_read_b128 v[214:217], v214 offset:3072
	global_load_lds_dwordx4 v[206:207], off
	v_lshl_add_u64 v[206:207], v[218:219], 0, s[14:15]
	s_add_i32 m0, s30, 0x2000
	s_nop 0
	global_load_lds_dwordx4 v[206:207], off
	s_barrier
	s_waitcnt lgkmcnt(0)
	s_waitcnt lgkmcnt(0)
	v_mfma_f32_16x16x32_bf16 v[108:111], v[198:201], v[166:169], v[108:111]
	v_mfma_f32_16x16x32_bf16 v[104:107], v[210:213], v[166:169], v[104:107]
	v_mfma_f32_16x16x32_bf16 v[92:95], v[198:201], v[174:177], v[92:95]
	v_mfma_f32_16x16x32_bf16 v[88:91], v[210:213], v[174:177], v[88:91]
	v_mfma_f32_16x16x32_bf16 v[76:79], v[198:201], v[182:185], v[76:79]
	v_mfma_f32_16x16x32_bf16 v[72:75], v[210:213], v[182:185], v[72:75]
	v_mfma_f32_16x16x32_bf16 v[68:71], v[198:201], v[190:193], v[68:71]
	v_mfma_f32_16x16x32_bf16 v[64:67], v[210:213], v[190:193], v[64:67]
	v_mfma_f32_16x16x32_bf16 v[108:111], v[202:205], v[170:173], v[108:111]
	v_mfma_f32_16x16x32_bf16 v[104:107], v[214:217], v[170:173], v[104:107]
	v_mfma_f32_16x16x32_bf16 v[92:95], v[202:205], v[178:181], v[92:95]
	v_mfma_f32_16x16x32_bf16 v[88:91], v[214:217], v[178:181], v[88:91]
	v_mfma_f32_16x16x32_bf16 v[76:79], v[202:205], v[186:189], v[76:79]
	v_mfma_f32_16x16x32_bf16 v[72:75], v[214:217], v[186:189], v[72:75]
	v_mfma_f32_16x16x32_bf16 v[68:71], v[202:205], v[194:197], v[68:71]
	v_mfma_f32_16x16x32_bf16 v[64:67], v[214:217], v[194:197], v[64:67]
	s_mov_b32 m0, s52
	v_lshl_add_u64 v[206:207], v[220:221], 0, s[14:15]
	s_barrier
	ds_read_b128 v[166:169], v148 offset:49152
	ds_read_b128 v[170:173], v148 offset:50176
	ds_read_b128 v[174:177], v148 offset:51200
	ds_read_b128 v[178:181], v148 offset:52224
	ds_read_b128 v[182:185], v148 offset:53248
	ds_read_b128 v[186:189], v148 offset:54272
	ds_read_b128 v[190:193], v148 offset:55296
	ds_read_b128 v[194:197], v148 offset:56320
	global_load_lds_dwordx4 v[206:207], off
	v_lshl_add_u64 v[206:207], v[222:223], 0, s[14:15]
	s_mov_b32 m0, s53
	s_nop 0
	global_load_lds_dwordx4 v[206:207], off
	s_barrier
	s_waitcnt lgkmcnt(0)
	s_waitcnt lgkmcnt(0)
	v_mfma_f32_16x16x32_bf16 v[60:63], v[150:153], v[166:169], v[60:63]
	v_mfma_f32_16x16x32_bf16 v[56:59], v[158:161], v[166:169], v[56:59]
	v_mfma_f32_16x16x32_bf16 v[52:55], v[150:153], v[174:177], v[52:55]
	v_mfma_f32_16x16x32_bf16 v[48:51], v[158:161], v[174:177], v[48:51]
	v_mfma_f32_16x16x32_bf16 v[36:39], v[150:153], v[182:185], v[36:39]
	v_mfma_f32_16x16x32_bf16 v[32:35], v[158:161], v[182:185], v[32:35]
	v_mfma_f32_16x16x32_bf16 v[20:23], v[150:153], v[190:193], v[20:23]
	v_mfma_f32_16x16x32_bf16 v[16:19], v[158:161], v[190:193], v[16:19]
	v_mfma_f32_16x16x32_bf16 v[60:63], v[154:157], v[170:173], v[60:63]
	v_mfma_f32_16x16x32_bf16 v[56:59], v[162:165], v[170:173], v[56:59]
	v_mfma_f32_16x16x32_bf16 v[52:55], v[154:157], v[178:181], v[52:55]
	v_mfma_f32_16x16x32_bf16 v[48:51], v[162:165], v[178:181], v[48:51]
	v_mfma_f32_16x16x32_bf16 v[36:39], v[154:157], v[186:189], v[36:39]
	v_mfma_f32_16x16x32_bf16 v[32:35], v[162:165], v[186:189], v[32:35]
	v_mfma_f32_16x16x32_bf16 v[20:23], v[154:157], v[194:197], v[20:23]
	v_mfma_f32_16x16x32_bf16 v[16:19], v[162:165], v[194:197], v[16:19]
	s_barrier
	s_add_u32 s30, s36, 0xa0080
	s_addc_u32 s31, s37, 0
	s_add_i32 s36, s38, s40
	v_lshl_add_u64 v[150:151], s[30:31], 0, v[130:131]
	s_mov_b32 m0, s36
	s_nop 0
	global_load_lds_dwordx4 v[150:151], off
	v_lshl_add_u64 v[150:151], s[30:31], 0, v[134:135]
	s_add_i32 m0, s36, 0x2000
	s_nop 0
	global_load_lds_dwordx4 v[150:151], off
	s_waitcnt vmcnt(6)
	s_barrier
	v_mfma_f32_16x16x32_bf16 v[44:47], v[198:201], v[166:169], v[44:47]
	v_mfma_f32_16x16x32_bf16 v[40:43], v[210:213], v[166:169], v[40:43]
	v_mfma_f32_16x16x32_bf16 v[28:31], v[198:201], v[174:177], v[28:31]
	v_mfma_f32_16x16x32_bf16 v[24:27], v[210:213], v[174:177], v[24:27]
	v_mfma_f32_16x16x32_bf16 v[12:15], v[198:201], v[182:185], v[12:15]
	v_mfma_f32_16x16x32_bf16 v[8:11], v[210:213], v[182:185], v[8:11]
	v_mfma_f32_16x16x32_bf16 v[4:7], v[198:201], v[190:193], v[4:7]
	v_mfma_f32_16x16x32_bf16 v[0:3], v[210:213], v[190:193], v[0:3]
	v_mfma_f32_16x16x32_bf16 v[44:47], v[202:205], v[170:173], v[44:47]
	v_mfma_f32_16x16x32_bf16 v[40:43], v[214:217], v[170:173], v[40:43]
	v_mfma_f32_16x16x32_bf16 v[28:31], v[202:205], v[178:181], v[28:31]
	v_mfma_f32_16x16x32_bf16 v[24:27], v[214:217], v[178:181], v[24:27]
	v_mfma_f32_16x16x32_bf16 v[12:15], v[202:205], v[186:189], v[12:15]
	v_mfma_f32_16x16x32_bf16 v[8:11], v[214:217], v[186:189], v[8:11]
	v_mfma_f32_16x16x32_bf16 v[4:7], v[202:205], v[194:197], v[4:7]
	v_mfma_f32_16x16x32_bf16 v[0:3], v[214:217], v[194:197], v[0:3]
	s_add_i32 s69, s69, 2
	s_add_u32 s67, s67, 0x100
	s_addc_u32 s68, s68, 0
	s_cmp_gt_u32 s69, 37
	s_mov_b64 s[30:31], s[34:35]
	s_barrier
	s_cbranch_scc0 .LBB0_1402
	v_mov_b32_e32 v150, v145
	v_mov_b32_e32 v151, v144
	s_lshl_b32 s30, s63, 8
	s_add_i32 s30, s30, s49
	v_add_u32_e32 v150, s30, v150
	s_lshl_b32 s30, s66, 8
	s_or_b32 s30, s30, s51
	v_lshl_add_u32 v152, v151, 3, s30
	v_ashrrev_i32_e32 v151, 31, v150
	v_lshlrev_b64 v[150:151], 12, v[150:151]
	v_ashrrev_i32_e32 v153, 31, v152
	v_lshl_add_u64 v[150:151], s[10:11], 0, v[150:151]
	v_lshl_add_u64 v[150:151], v[152:153], 1, v[150:151]
	v_cvt_pk_bf16_f32 v108, v108, v109
	v_cvt_pk_bf16_f32 v109, v110, v111
	v_cvt_pk_bf16_f32 v110, v104, v105
	v_cvt_pk_bf16_f32 v111, v106, v107
	global_store_dwordx4 v[150:151], v[108:111], off offset:256
	v_cvt_pk_bf16_f32 v92, v92, v93
	v_cvt_pk_bf16_f32 v93, v94, v95
	v_add_co_u32_e32 v110, vcc, s48, v150
	v_lshl_add_u64 v[108:109], v[150:151], 0, s[18:19]
	s_nop 0
	v_addc_co_u32_e32 v111, vcc, 0, v151, vcc
	v_cvt_pk_bf16_f32 v94, v88, v89
	v_cvt_pk_bf16_f32 v95, v90, v91
	global_store_dwordx4 v[108:109], v[92:95], off offset:256
	v_cvt_pk_bf16_f32 v76, v76, v77
	v_cvt_pk_bf16_f32 v77, v78, v79
	v_add_co_u32_e32 v94, vcc, s56, v150
	v_lshl_add_u64 v[92:93], v[150:151], 0, s[20:21]
	s_nop 0
	v_addc_co_u32_e32 v95, vcc, 0, v151, vcc
	v_cvt_pk_bf16_f32 v78, v72, v73
	v_cvt_pk_bf16_f32 v79, v74, v75
	global_store_dwordx4 v[92:93], v[76:79], off offset:256
	v_cvt_pk_bf16_f32 v60, v60, v61
	v_cvt_pk_bf16_f32 v61, v62, v63
	v_add_co_u32_e32 v78, vcc, s57, v150
	v_cvt_pk_bf16_f32 v62, v56, v57
	s_nop 0
	v_addc_co_u32_e32 v79, vcc, 0, v151, vcc
	v_add_co_u32_e32 v56, vcc, s59, v150
	v_cvt_pk_bf16_f32 v68, v68, v69
	v_cvt_pk_bf16_f32 v69, v70, v71
	v_cvt_pk_bf16_f32 v70, v64, v65
	v_lshl_add_u64 v[64:65], v[150:151], 0, s[24:25]
	v_addc_co_u32_e32 v57, vcc, 0, v151, vcc
	v_cvt_pk_bf16_f32 v44, v44, v45
	v_cvt_pk_bf16_f32 v45, v46, v47
	v_cvt_pk_bf16_f32 v46, v40, v41
	v_cvt_pk_bf16_f32 v47, v42, v43
	global_store_dwordx4 v[64:65], v[44:47], off offset:256
	v_cvt_pk_bf16_f32 v28, v28, v29
	v_cvt_pk_bf16_f32 v29, v30, v31
	v_add_co_u32_e32 v46, vcc, s60, v150
	v_lshl_add_u64 v[44:45], v[150:151], 0, s[26:27]
	s_nop 0
	v_addc_co_u32_e32 v47, vcc, 0, v151, vcc
	v_cvt_pk_bf16_f32 v30, v24, v25
	v_cvt_pk_bf16_f32 v31, v26, v27
	global_store_dwordx4 v[44:45], v[28:31], off offset:256
	v_cvt_pk_bf16_f32 v12, v12, v13
	v_cvt_pk_bf16_f32 v13, v14, v15
	v_add_co_u32_e32 v30, vcc, s61, v150
	v_lshl_add_u64 v[28:29], v[150:151], 0, s[8:9]
	s_nop 0
	v_addc_co_u32_e32 v31, vcc, 0, v151, vcc
	v_cvt_pk_bf16_f32 v14, v8, v9
	v_cvt_pk_bf16_f32 v15, v10, v11
	global_store_dwordx4 v[28:29], v[12:15], off offset:256
	v_cvt_pk_bf16_f32 v124, v124, v125
	v_cvt_pk_bf16_f32 v125, v126, v127
	v_add_co_u32_e32 v14, vcc, s62, v150
	v_cvt_pk_bf16_f32 v126, v120, v121
	s_nop 0
	v_addc_co_u32_e32 v15, vcc, 0, v151, vcc
	v_cvt_pk_bf16_f32 v127, v122, v123
	v_cvt_pk_bf16_f32 v104, v116, v117
	v_cvt_pk_bf16_f32 v105, v118, v119
	v_cvt_pk_bf16_f32 v106, v112, v113
	v_cvt_pk_bf16_f32 v107, v114, v115
	v_cvt_pk_bf16_f32 v88, v100, v101
	v_cvt_pk_bf16_f32 v89, v102, v103
	v_cvt_pk_bf16_f32 v90, v96, v97
	v_cvt_pk_bf16_f32 v91, v98, v99
	v_lshl_add_u64 v[76:77], v[150:151], 0, s[22:23]
	v_cvt_pk_bf16_f32 v72, v84, v85
	v_cvt_pk_bf16_f32 v73, v86, v87
	v_cvt_pk_bf16_f32 v74, v80, v81
	v_cvt_pk_bf16_f32 v75, v82, v83
	v_cvt_pk_bf16_f32 v71, v66, v67
	v_cvt_pk_bf16_f32 v63, v58, v59
	v_cvt_pk_bf16_f32 v40, v52, v53
	v_cvt_pk_bf16_f32 v41, v54, v55
	v_cvt_pk_bf16_f32 v42, v48, v49
	v_cvt_pk_bf16_f32 v43, v50, v51
	v_cvt_pk_bf16_f32 v24, v36, v37
	v_cvt_pk_bf16_f32 v25, v38, v39
	v_cvt_pk_bf16_f32 v26, v32, v33
	v_cvt_pk_bf16_f32 v27, v34, v35
	v_lshl_add_u64 v[12:13], v[150:151], 0, s[28:29]
	v_cvt_pk_bf16_f32 v8, v20, v21
	v_cvt_pk_bf16_f32 v9, v22, v23
	v_cvt_pk_bf16_f32 v10, v16, v17
	v_cvt_pk_bf16_f32 v11, v18, v19
	v_cvt_pk_bf16_f32 v4, v4, v5
	v_cvt_pk_bf16_f32 v5, v6, v7
	v_cvt_pk_bf16_f32 v6, v0, v1
	v_cvt_pk_bf16_f32 v7, v2, v3
	s_and_b64 vcc, exec, s[2:3]
	s_mov_b32 s66, s64
	s_mov_b32 s63, s65
	s_mov_b64 s[34:35], s[6:7]
	s_mov_b64 s[30:31], s[4:5]
	global_store_dwordx4 v[150:151], v[124:127], off
	global_store_dwordx4 v[110:111], v[104:107], off
	global_store_dwordx4 v[94:95], v[88:91], off
	global_store_dwordx4 v[78:79], v[72:75], off
	global_store_dwordx4 v[76:77], v[68:71], off offset:256
	global_store_dwordx4 v[56:57], v[60:63], off
	global_store_dwordx4 v[46:47], v[40:43], off
	global_store_dwordx4 v[30:31], v[24:27], off
	global_store_dwordx4 v[14:15], v[8:11], off
	global_store_dwordx4 v[12:13], v[4:7], off offset:256
	s_cbranch_vccz .LBB0_1391
	s_waitcnt vmcnt(0)
	s_cmpk_gt_u32 s33, 0xff
	s_cbranch_scc1 .LBB0_1406
	s_barrier
